# v67 + K-loops: 34 LDS-DMA address adds folded into SGPR-base addressing (one 64-bit VALU add less per DMA)
# speedup vs baseline: 1.0055x; 1.0055x over previous
.LBB0_267:
	s_add_i32 m0, s7, 0xc000
	ds_read_b128 v[160:163], v151
	ds_read_b128 v[164:167], v151 offset:1024
	ds_read_b128 v[168:171], v151 offset:2048
	ds_read_b128 v[172:175], v151 offset:3072
	ds_read_b128 v[176:179], v151 offset:4096
	ds_read_b128 v[180:183], v151 offset:5120
	ds_read_b128 v[184:187], v151 offset:6144
	ds_read_b128 v[190:193], v151 offset:7168
	global_load_lds_dwordx4 v138, s[4:5]
	s_add_i32 m0, s7, 0xe000
	s_nop 0
	global_load_lds_dwordx4 v140, s[4:5]
	s_waitcnt lgkmcnt(8)
	s_barrier
	s_waitcnt lgkmcnt(0)
	v_mfma_f32_16x16x32_bf16 v[126:129], v[142:145], v[160:163], v[126:129]
	v_mfma_f32_16x16x32_bf16 v[122:125], v[152:155], v[160:163], v[122:125]
	v_mfma_f32_16x16x32_bf16 v[110:113], v[142:145], v[168:171], v[110:113]
	v_mfma_f32_16x16x32_bf16 v[106:109], v[152:155], v[168:171], v[106:109]
	v_mfma_f32_16x16x32_bf16 v[94:97], v[142:145], v[176:179], v[94:97]
	v_mfma_f32_16x16x32_bf16 v[90:93], v[152:155], v[176:179], v[90:93]
	v_mfma_f32_16x16x32_bf16 v[78:81], v[142:145], v[184:187], v[78:81]
	v_mfma_f32_16x16x32_bf16 v[74:77], v[152:155], v[184:187], v[74:77]
	v_mfma_f32_16x16x32_bf16 v[126:129], v[146:149], v[164:167], v[126:129]
	v_mfma_f32_16x16x32_bf16 v[122:125], v[156:159], v[164:167], v[122:125]
	v_mfma_f32_16x16x32_bf16 v[110:113], v[146:149], v[172:175], v[110:113]
	v_mfma_f32_16x16x32_bf16 v[106:109], v[156:159], v[172:175], v[106:109]
	v_mfma_f32_16x16x32_bf16 v[94:97], v[146:149], v[180:183], v[94:97]
	v_mfma_f32_16x16x32_bf16 v[90:93], v[156:159], v[180:183], v[90:93]
	v_mfma_f32_16x16x32_bf16 v[78:81], v[146:149], v[190:193], v[78:81]
	v_mfma_f32_16x16x32_bf16 v[74:77], v[156:159], v[190:193], v[74:77]
	s_barrier
	s_add_i32 s88, 0, 0x14000
	s_add_i32 s86, s86, s22
	v_add_u32_e32 v0, s88, v150
	v_lshl_add_u64 v[210:211], s[12:13], 0, v[134:135]
	s_mov_b32 m0, s86
	ds_read_b128 v[194:197], v0
	ds_read_b128 v[198:201], v0 offset:1024
	ds_read_b128 v[202:205], v0 offset:2048
	ds_read_b128 v[206:209], v0 offset:3072
	global_load_lds_dwordx4 v[210:211], off
	s_add_i32 m0, s86, 0x2000
	v_lshl_add_u64 v[212:213], s[12:13], 0, v[130:131]
	global_load_lds_dwordx4 v[212:213], off
	s_barrier
	s_waitcnt lgkmcnt(0)
	v_mfma_f32_16x16x32_bf16 v[118:121], v[194:197], v[160:163], v[118:121]
	v_mfma_f32_16x16x32_bf16 v[114:117], v[202:205], v[160:163], v[114:117]
	v_mfma_f32_16x16x32_bf16 v[102:105], v[194:197], v[168:171], v[102:105]
	v_mfma_f32_16x16x32_bf16 v[98:101], v[202:205], v[168:171], v[98:101]
	v_mfma_f32_16x16x32_bf16 v[86:89], v[194:197], v[176:179], v[86:89]
	v_mfma_f32_16x16x32_bf16 v[82:85], v[202:205], v[176:179], v[82:85]
	v_mfma_f32_16x16x32_bf16 v[70:73], v[194:197], v[184:187], v[70:73]
	v_mfma_f32_16x16x32_bf16 v[66:69], v[202:205], v[184:187], v[66:69]
	v_mfma_f32_16x16x32_bf16 v[118:121], v[198:201], v[164:167], v[118:121]
	v_mfma_f32_16x16x32_bf16 v[114:117], v[206:209], v[164:167], v[114:117]
	v_mfma_f32_16x16x32_bf16 v[102:105], v[198:201], v[172:175], v[102:105]
	v_mfma_f32_16x16x32_bf16 v[98:101], v[206:209], v[172:175], v[98:101]
	v_mfma_f32_16x16x32_bf16 v[86:89], v[198:201], v[180:183], v[86:89]
	v_mfma_f32_16x16x32_bf16 v[82:85], v[206:209], v[180:183], v[82:85]
	v_mfma_f32_16x16x32_bf16 v[70:73], v[198:201], v[190:193], v[70:73]
	v_mfma_f32_16x16x32_bf16 v[66:69], v[206:209], v[190:193], v[66:69]
	s_mov_b32 m0, s7
	v_lshl_add_u64 v[214:215], s[14:15], 0, v[136:137]
	s_barrier
	ds_read_b128 v[160:163], v151 offset:16384
	ds_read_b128 v[164:167], v151 offset:17408
	ds_read_b128 v[168:171], v151 offset:18432
	ds_read_b128 v[172:175], v151 offset:19456
	ds_read_b128 v[176:179], v151 offset:20480
	ds_read_b128 v[180:183], v151 offset:21504
	ds_read_b128 v[184:187], v151 offset:22528
	ds_read_b128 v[190:193], v151 offset:23552
	global_load_lds_dwordx4 v[214:215], off
	s_mov_b32 m0, s23
	v_lshl_add_u64 v[216:217], s[14:15], 0, v[132:133]
	global_load_lds_dwordx4 v[216:217], off
	s_waitcnt vmcnt(10)
	s_barrier
	s_waitcnt lgkmcnt(0)
	v_mfma_f32_16x16x32_bf16 v[62:65], v[142:145], v[160:163], v[62:65]
	v_mfma_f32_16x16x32_bf16 v[58:61], v[152:155], v[160:163], v[58:61]
	v_mfma_f32_16x16x32_bf16 v[46:49], v[142:145], v[168:171], v[46:49]
	v_mfma_f32_16x16x32_bf16 v[42:45], v[152:155], v[168:171], v[42:45]
	v_mfma_f32_16x16x32_bf16 v[30:33], v[142:145], v[176:179], v[30:33]
	v_mfma_f32_16x16x32_bf16 v[26:29], v[152:155], v[176:179], v[26:29]
	v_mfma_f32_16x16x32_bf16 v[14:17], v[142:145], v[184:187], v[14:17]
	v_mfma_f32_16x16x32_bf16 v[10:13], v[152:155], v[184:187], v[10:13]
	v_mfma_f32_16x16x32_bf16 v[62:65], v[146:149], v[164:167], v[62:65]
	v_mfma_f32_16x16x32_bf16 v[58:61], v[156:159], v[164:167], v[58:61]
	v_mfma_f32_16x16x32_bf16 v[46:49], v[146:149], v[172:175], v[46:49]
	v_mfma_f32_16x16x32_bf16 v[42:45], v[156:159], v[172:175], v[42:45]
	v_mfma_f32_16x16x32_bf16 v[30:33], v[146:149], v[180:183], v[30:33]
	v_mfma_f32_16x16x32_bf16 v[26:29], v[156:159], v[180:183], v[26:29]
	v_mfma_f32_16x16x32_bf16 v[14:17], v[146:149], v[190:193], v[14:17]
	v_mfma_f32_16x16x32_bf16 v[10:13], v[156:159], v[190:193], v[10:13]
	s_barrier
	s_add_u32 s86, s12, 0x40000
	s_addc_u32 s87, s13, 0
	s_add_i32 s88, s88, s22
	s_mov_b32 m0, s88
	s_nop 0
	global_load_lds_dwordx4 v134, s[86:87]
	s_add_i32 m0, s88, 0x2000
	s_nop 0
	global_load_lds_dwordx4 v130, s[86:87]
	s_add_i32 s86, 0, 0x18000
	v_add_u32_e32 v0, s86, v150
	ds_read_b128 v[142:145], v0
	ds_read_b128 v[146:149], v0 offset:1024
	ds_read_b128 v[152:155], v0 offset:2048
	ds_read_b128 v[156:159], v0 offset:3072
	s_waitcnt vmcnt(6)
	s_barrier
	v_mfma_f32_16x16x32_bf16 v[54:57], v[194:197], v[160:163], v[54:57]
	v_mfma_f32_16x16x32_bf16 v[50:53], v[202:205], v[160:163], v[50:53]
	v_mfma_f32_16x16x32_bf16 v[38:41], v[194:197], v[168:171], v[38:41]
	v_mfma_f32_16x16x32_bf16 v[34:37], v[202:205], v[168:171], v[34:37]
	v_mfma_f32_16x16x32_bf16 v[22:25], v[194:197], v[176:179], v[22:25]
	v_mfma_f32_16x16x32_bf16 v[18:21], v[202:205], v[176:179], v[18:21]
	v_mfma_f32_16x16x32_bf16 v[6:9], v[194:197], v[184:187], v[6:9]
	v_mfma_f32_16x16x32_bf16 v[2:5], v[202:205], v[184:187], v[2:5]
	v_mfma_f32_16x16x32_bf16 v[54:57], v[198:201], v[164:167], v[54:57]
	v_mfma_f32_16x16x32_bf16 v[50:53], v[206:209], v[164:167], v[50:53]
	v_mfma_f32_16x16x32_bf16 v[38:41], v[198:201], v[172:175], v[38:41]
	v_mfma_f32_16x16x32_bf16 v[34:37], v[206:209], v[172:175], v[34:37]
	v_mfma_f32_16x16x32_bf16 v[22:25], v[198:201], v[180:183], v[22:25]
	v_mfma_f32_16x16x32_bf16 v[18:21], v[206:209], v[180:183], v[18:21]
	v_mfma_f32_16x16x32_bf16 v[6:9], v[198:201], v[190:193], v[6:9]
	v_mfma_f32_16x16x32_bf16 v[2:5], v[206:209], v[190:193], v[2:5]
	s_barrier
	s_add_u32 s14, s14, 0x40000
	s_addc_u32 s15, s15, 0
	s_mov_b32 m0, s28
	ds_read_b128 v[160:163], v151 offset:32768
	ds_read_b128 v[164:167], v151 offset:33792
	ds_read_b128 v[168:171], v151 offset:34816
	ds_read_b128 v[172:175], v151 offset:35840
	ds_read_b128 v[176:179], v151 offset:36864
	ds_read_b128 v[180:183], v151 offset:37888
	ds_read_b128 v[184:187], v151 offset:38912
	ds_read_b128 v[190:193], v151 offset:39936
	global_load_lds_dwordx4 v136, s[14:15]
	s_mov_b32 m0, s29
	s_nop 0
	global_load_lds_dwordx4 v132, s[14:15]
	s_waitcnt lgkmcnt(8)
	s_barrier
	s_waitcnt lgkmcnt(0)
	v_mfma_f32_16x16x32_bf16 v[126:129], v[142:145], v[160:163], v[126:129]
	v_mfma_f32_16x16x32_bf16 v[122:125], v[152:155], v[160:163], v[122:125]
	v_mfma_f32_16x16x32_bf16 v[110:113], v[142:145], v[168:171], v[110:113]
	v_mfma_f32_16x16x32_bf16 v[106:109], v[152:155], v[168:171], v[106:109]
	v_mfma_f32_16x16x32_bf16 v[94:97], v[142:145], v[176:179], v[94:97]
	v_mfma_f32_16x16x32_bf16 v[90:93], v[152:155], v[176:179], v[90:93]
	v_mfma_f32_16x16x32_bf16 v[78:81], v[142:145], v[184:187], v[78:81]
	v_mfma_f32_16x16x32_bf16 v[74:77], v[152:155], v[184:187], v[74:77]
	v_mfma_f32_16x16x32_bf16 v[126:129], v[146:149], v[164:167], v[126:129]
	v_mfma_f32_16x16x32_bf16 v[122:125], v[156:159], v[164:167], v[122:125]
	v_mfma_f32_16x16x32_bf16 v[110:113], v[146:149], v[172:175], v[110:113]
	v_mfma_f32_16x16x32_bf16 v[106:109], v[156:159], v[172:175], v[106:109]
	v_mfma_f32_16x16x32_bf16 v[94:97], v[146:149], v[180:183], v[94:97]
	v_mfma_f32_16x16x32_bf16 v[90:93], v[156:159], v[180:183], v[90:93]
	v_mfma_f32_16x16x32_bf16 v[78:81], v[146:149], v[190:193], v[78:81]
	v_mfma_f32_16x16x32_bf16 v[74:77], v[156:159], v[190:193], v[74:77]
	s_barrier
	s_add_i32 s14, 0, 0x1c000
	s_add_i32 s15, s86, s22
	v_add_u32_e32 v0, s14, v150
	v_lshl_add_u64 v[210:211], v[210:211], 0, s[40:41]
	s_mov_b32 m0, s15
	ds_read_b128 v[194:197], v0
	ds_read_b128 v[198:201], v0 offset:1024
	ds_read_b128 v[202:205], v0 offset:2048
	ds_read_b128 v[206:209], v0 offset:3072
	global_load_lds_dwordx4 v[210:211], off
	s_add_i32 m0, s15, 0x2000
	v_lshl_add_u64 v[210:211], v[212:213], 0, s[40:41]
	global_load_lds_dwordx4 v[210:211], off
	s_barrier
	s_waitcnt lgkmcnt(0)
	v_mfma_f32_16x16x32_bf16 v[118:121], v[194:197], v[160:163], v[118:121]
	v_mfma_f32_16x16x32_bf16 v[114:117], v[202:205], v[160:163], v[114:117]
	v_mfma_f32_16x16x32_bf16 v[102:105], v[194:197], v[168:171], v[102:105]
	v_mfma_f32_16x16x32_bf16 v[98:101], v[202:205], v[168:171], v[98:101]
	v_mfma_f32_16x16x32_bf16 v[86:89], v[194:197], v[176:179], v[86:89]
	v_mfma_f32_16x16x32_bf16 v[82:85], v[202:205], v[176:179], v[82:85]
	v_mfma_f32_16x16x32_bf16 v[70:73], v[194:197], v[184:187], v[70:73]
	v_mfma_f32_16x16x32_bf16 v[66:69], v[202:205], v[184:187], v[66:69]
	v_mfma_f32_16x16x32_bf16 v[118:121], v[198:201], v[164:167], v[118:121]
	v_mfma_f32_16x16x32_bf16 v[114:117], v[206:209], v[164:167], v[114:117]
	v_mfma_f32_16x16x32_bf16 v[102:105], v[198:201], v[172:175], v[102:105]
	v_mfma_f32_16x16x32_bf16 v[98:101], v[206:209], v[172:175], v[98:101]
	v_mfma_f32_16x16x32_bf16 v[86:89], v[198:201], v[180:183], v[86:89]
	v_mfma_f32_16x16x32_bf16 v[82:85], v[206:209], v[180:183], v[82:85]
	v_mfma_f32_16x16x32_bf16 v[70:73], v[198:201], v[190:193], v[70:73]
	v_mfma_f32_16x16x32_bf16 v[66:69], v[206:209], v[190:193], v[66:69]
	s_mov_b32 m0, s38
	v_lshl_add_u64 v[210:211], v[214:215], 0, s[40:41]
	s_barrier
	ds_read_b128 v[160:163], v151 offset:49152
	ds_read_b128 v[164:167], v151 offset:50176
	ds_read_b128 v[168:171], v151 offset:51200
	ds_read_b128 v[172:175], v151 offset:52224
	ds_read_b128 v[176:179], v151 offset:53248
	ds_read_b128 v[180:183], v151 offset:54272
	ds_read_b128 v[184:187], v151 offset:55296
	ds_read_b128 v[190:193], v151 offset:56320
	global_load_lds_dwordx4 v[210:211], off
	s_mov_b32 m0, s39
	v_lshl_add_u64 v[210:211], v[216:217], 0, s[40:41]
	global_load_lds_dwordx4 v[210:211], off
	s_waitcnt vmcnt(10)
	s_barrier
	s_waitcnt lgkmcnt(0)
	v_mfma_f32_16x16x32_bf16 v[62:65], v[142:145], v[160:163], v[62:65]
	v_mfma_f32_16x16x32_bf16 v[58:61], v[152:155], v[160:163], v[58:61]
	v_mfma_f32_16x16x32_bf16 v[46:49], v[142:145], v[168:171], v[46:49]
	v_mfma_f32_16x16x32_bf16 v[42:45], v[152:155], v[168:171], v[42:45]
	v_mfma_f32_16x16x32_bf16 v[30:33], v[142:145], v[176:179], v[30:33]
	v_mfma_f32_16x16x32_bf16 v[26:29], v[152:155], v[176:179], v[26:29]
	v_mfma_f32_16x16x32_bf16 v[14:17], v[142:145], v[184:187], v[14:17]
	v_mfma_f32_16x16x32_bf16 v[10:13], v[152:155], v[184:187], v[10:13]
	v_mfma_f32_16x16x32_bf16 v[62:65], v[146:149], v[164:167], v[62:65]
	v_mfma_f32_16x16x32_bf16 v[58:61], v[156:159], v[164:167], v[58:61]
	v_mfma_f32_16x16x32_bf16 v[46:49], v[146:149], v[172:175], v[46:49]
	v_mfma_f32_16x16x32_bf16 v[42:45], v[156:159], v[172:175], v[42:45]
	v_mfma_f32_16x16x32_bf16 v[30:33], v[146:149], v[180:183], v[30:33]
	v_mfma_f32_16x16x32_bf16 v[26:29], v[156:159], v[180:183], v[26:29]
	v_mfma_f32_16x16x32_bf16 v[14:17], v[146:149], v[190:193], v[14:17]
	v_mfma_f32_16x16x32_bf16 v[10:13], v[156:159], v[190:193], v[10:13]
	s_barrier
	s_add_u32 s12, s12, 0x40080
	s_addc_u32 s13, s13, 0
	s_add_i32 s14, s14, s22
	s_mov_b32 m0, s14
	s_nop 0
	global_load_lds_dwordx4 v134, s[12:13]
	s_add_i32 m0, s14, 0x2000
	s_nop 0
	global_load_lds_dwordx4 v130, s[12:13]
	s_add_i32 s86, 0, 0x10000
	v_add_u32_e32 v0, s86, v150
	ds_read_b128 v[142:145], v0
	ds_read_b128 v[146:149], v0 offset:1024
	ds_read_b128 v[152:155], v0 offset:2048
	ds_read_b128 v[156:159], v0 offset:3072
	s_waitcnt vmcnt(6)
	s_barrier
	v_mfma_f32_16x16x32_bf16 v[54:57], v[194:197], v[160:163], v[54:57]
	v_mfma_f32_16x16x32_bf16 v[50:53], v[202:205], v[160:163], v[50:53]
	v_mfma_f32_16x16x32_bf16 v[38:41], v[194:197], v[168:171], v[38:41]
	v_mfma_f32_16x16x32_bf16 v[34:37], v[202:205], v[168:171], v[34:37]
	v_mfma_f32_16x16x32_bf16 v[22:25], v[194:197], v[176:179], v[22:25]
	v_mfma_f32_16x16x32_bf16 v[18:21], v[202:205], v[176:179], v[18:21]
	v_mfma_f32_16x16x32_bf16 v[6:9], v[194:197], v[184:187], v[6:9]
	v_mfma_f32_16x16x32_bf16 v[2:5], v[202:205], v[184:187], v[2:5]
	v_mfma_f32_16x16x32_bf16 v[54:57], v[198:201], v[164:167], v[54:57]
	v_mfma_f32_16x16x32_bf16 v[50:53], v[206:209], v[164:167], v[50:53]
	v_mfma_f32_16x16x32_bf16 v[38:41], v[198:201], v[172:175], v[38:41]
	v_mfma_f32_16x16x32_bf16 v[34:37], v[206:209], v[172:175], v[34:37]
	v_mfma_f32_16x16x32_bf16 v[22:25], v[198:201], v[180:183], v[22:25]
	v_mfma_f32_16x16x32_bf16 v[18:21], v[206:209], v[180:183], v[18:21]
	v_mfma_f32_16x16x32_bf16 v[6:9], v[198:201], v[190:193], v[6:9]
	v_mfma_f32_16x16x32_bf16 v[2:5], v[206:209], v[190:193], v[2:5]
	s_add_i32 s85, s85, 2
	s_add_u32 s4, s4, 0x100
	s_addc_u32 s5, s5, 0
	s_add_u32 s78, s78, 0x100
	s_addc_u32 s79, s79, 0
	s_add_u32 s12, s4, 0xfffc0080
	s_addc_u32 s13, s5, -1
	s_cmp_eq_u32 s85, 12
	s_cselect_b32 s15, s44, s13
	s_cselect_b32 s14, s45, s12
	s_cselect_b32 s13, s47, s79
	s_cselect_b32 s12, s55, s78
	s_cmp_gt_u32 s85, 13
	s_barrier
	s_cbranch_scc0 .LBB0_267
	s_waitcnt lgkmcnt(0)
	v_mov_b32_e32 v156, v252
	s_mov_b64 s[4:5], -1
	v_and_b32_e32 v154, 63, v156
	s_andn2_b64 vcc, exec, s[2:3]
	v_lshlrev_b32_e32 v142, 2, v154
	s_cbranch_vccnz .LBB0_270
	v_lshlrev_b32_e32 v155, 2, v154
	s_mov_b64 s[4:5], 0

.LBB0_838:
	v_lshl_add_u64 v[178:179], s[88:89], 0, v[196:197]
	s_add_i32 m0, s39, 0xc000
	ds_read_b128 v[146:149], v213
	ds_read_b128 v[150:153], v213 offset:1024
	ds_read_b128 v[154:157], v213 offset:2048
	ds_read_b128 v[158:161], v213 offset:3072
	ds_read_b128 v[162:165], v213 offset:4096
	ds_read_b128 v[166:169], v213 offset:5120
	ds_read_b128 v[170:173], v213 offset:6144
	ds_read_b128 v[174:177], v213 offset:7168
	global_load_lds_dwordx4 v[178:179], off
	s_add_i32 m0, s39, 0xe000
	v_lshl_add_u64 v[178:179], s[88:89], 0, v[198:199]
	global_load_lds_dwordx4 v[178:179], off
	s_waitcnt lgkmcnt(8)
	s_barrier
	s_waitcnt lgkmcnt(0)
	v_mfma_f32_16x16x32_bf16 v[126:129], v[130:133], v[146:149], v[126:129]
	v_mfma_f32_16x16x32_bf16 v[122:125], v[138:141], v[146:149], v[122:125]
	v_mfma_f32_16x16x32_bf16 v[110:113], v[130:133], v[154:157], v[110:113]
	v_mfma_f32_16x16x32_bf16 v[106:109], v[138:141], v[154:157], v[106:109]
	v_mfma_f32_16x16x32_bf16 v[94:97], v[130:133], v[162:165], v[94:97]
	v_mfma_f32_16x16x32_bf16 v[90:93], v[138:141], v[162:165], v[90:93]
	v_mfma_f32_16x16x32_bf16 v[78:81], v[130:133], v[170:173], v[78:81]
	v_mfma_f32_16x16x32_bf16 v[74:77], v[138:141], v[170:173], v[74:77]
	v_mfma_f32_16x16x32_bf16 v[126:129], v[134:137], v[150:153], v[126:129]
	v_mfma_f32_16x16x32_bf16 v[122:125], v[142:145], v[150:153], v[122:125]
	v_mfma_f32_16x16x32_bf16 v[110:113], v[134:137], v[158:161], v[110:113]
	v_mfma_f32_16x16x32_bf16 v[106:109], v[142:145], v[158:161], v[106:109]
	v_mfma_f32_16x16x32_bf16 v[94:97], v[134:137], v[166:169], v[94:97]
	v_mfma_f32_16x16x32_bf16 v[90:93], v[142:145], v[166:169], v[90:93]
	v_mfma_f32_16x16x32_bf16 v[78:81], v[134:137], v[174:177], v[78:81]
	v_mfma_f32_16x16x32_bf16 v[74:77], v[142:145], v[174:177], v[74:77]
	s_barrier
	s_add_i32 s87, 0, 0x14000
	v_add_u32_e32 v186, s87, v212
	s_add_i32 s79, s79, s38
	ds_read_b128 v[178:181], v186
	ds_read_b128 v[182:185], v186 offset:1024
	ds_read_b128 v[200:203], v186 offset:2048
	ds_read_b128 v[204:207], v186 offset:3072
	v_lshl_add_u64 v[186:187], s[90:91], 0, v[0:1]
	s_mov_b32 m0, s79
	v_lshl_add_u64 v[208:209], s[90:91], 0, v[194:195]
	global_load_lds_dwordx4 v[186:187], off
	s_add_i32 m0, s79, 0x2000
	s_nop 0
	global_load_lds_dwordx4 v[208:209], off
	s_barrier
	s_waitcnt lgkmcnt(0)
	v_mfma_f32_16x16x32_bf16 v[118:121], v[178:181], v[146:149], v[118:121]
	v_mfma_f32_16x16x32_bf16 v[114:117], v[200:203], v[146:149], v[114:117]
	v_mfma_f32_16x16x32_bf16 v[102:105], v[178:181], v[154:157], v[102:105]
	v_mfma_f32_16x16x32_bf16 v[98:101], v[200:203], v[154:157], v[98:101]
	v_mfma_f32_16x16x32_bf16 v[86:89], v[178:181], v[162:165], v[86:89]
	v_mfma_f32_16x16x32_bf16 v[82:85], v[200:203], v[162:165], v[82:85]
	v_mfma_f32_16x16x32_bf16 v[70:73], v[178:181], v[170:173], v[70:73]
	v_mfma_f32_16x16x32_bf16 v[66:69], v[200:203], v[170:173], v[66:69]
	v_mfma_f32_16x16x32_bf16 v[118:121], v[182:185], v[150:153], v[118:121]
	v_mfma_f32_16x16x32_bf16 v[114:117], v[204:207], v[150:153], v[114:117]
	v_mfma_f32_16x16x32_bf16 v[102:105], v[182:185], v[158:161], v[102:105]
	v_mfma_f32_16x16x32_bf16 v[98:101], v[204:207], v[158:161], v[98:101]
	v_mfma_f32_16x16x32_bf16 v[86:89], v[182:185], v[166:169], v[86:89]
	v_mfma_f32_16x16x32_bf16 v[82:85], v[204:207], v[166:169], v[82:85]
	v_mfma_f32_16x16x32_bf16 v[70:73], v[182:185], v[174:177], v[70:73]
	v_mfma_f32_16x16x32_bf16 v[66:69], v[204:207], v[174:177], v[66:69]
	s_mov_b32 m0, s39
	v_lshl_add_u64 v[210:211], s[92:93], 0, v[190:191]
	s_barrier
	ds_read_b128 v[146:149], v213 offset:16384
	ds_read_b128 v[150:153], v213 offset:17408
	ds_read_b128 v[154:157], v213 offset:18432
	ds_read_b128 v[158:161], v213 offset:19456
	ds_read_b128 v[162:165], v213 offset:20480
	ds_read_b128 v[166:169], v213 offset:21504
	ds_read_b128 v[170:173], v213 offset:22528
	ds_read_b128 v[174:177], v213 offset:23552
	global_load_lds_dwordx4 v[210:211], off
	s_mov_b32 m0, s42
	v_lshl_add_u64 v[214:215], s[92:93], 0, v[192:193]
	global_load_lds_dwordx4 v[214:215], off
	s_waitcnt vmcnt(10)
	s_barrier
	s_waitcnt lgkmcnt(0)
	v_mfma_f32_16x16x32_bf16 v[62:65], v[130:133], v[146:149], v[62:65]
	v_mfma_f32_16x16x32_bf16 v[58:61], v[138:141], v[146:149], v[58:61]
	v_mfma_f32_16x16x32_bf16 v[46:49], v[130:133], v[154:157], v[46:49]
	v_mfma_f32_16x16x32_bf16 v[42:45], v[138:141], v[154:157], v[42:45]
	v_mfma_f32_16x16x32_bf16 v[30:33], v[130:133], v[162:165], v[30:33]
	v_mfma_f32_16x16x32_bf16 v[26:29], v[138:141], v[162:165], v[26:29]
	v_mfma_f32_16x16x32_bf16 v[14:17], v[130:133], v[170:173], v[14:17]
	v_mfma_f32_16x16x32_bf16 v[10:13], v[138:141], v[170:173], v[10:13]
	v_mfma_f32_16x16x32_bf16 v[62:65], v[134:137], v[150:153], v[62:65]
	v_mfma_f32_16x16x32_bf16 v[58:61], v[142:145], v[150:153], v[58:61]
	v_mfma_f32_16x16x32_bf16 v[46:49], v[134:137], v[158:161], v[46:49]
	v_mfma_f32_16x16x32_bf16 v[42:45], v[142:145], v[158:161], v[42:45]
	v_mfma_f32_16x16x32_bf16 v[30:33], v[134:137], v[166:169], v[30:33]
	v_mfma_f32_16x16x32_bf16 v[26:29], v[142:145], v[166:169], v[26:29]
	v_mfma_f32_16x16x32_bf16 v[14:17], v[134:137], v[174:177], v[14:17]
	v_mfma_f32_16x16x32_bf16 v[10:13], v[142:145], v[174:177], v[10:13]
	s_barrier
	s_add_u32 s88, s90, 0x40000
	s_addc_u32 s89, s91, 0
	s_add_i32 s79, s87, s38
	s_mov_b32 m0, s79
	s_nop 0
	global_load_lds_dwordx4 v0, s[88:89]
	s_add_i32 m0, s79, 0x2000
	s_nop 0
	global_load_lds_dwordx4 v194, s[88:89]
	s_add_i32 s79, 0, 0x18000
	v_add_u32_e32 v142, s79, v212
	ds_read_b128 v[130:133], v142
	ds_read_b128 v[134:137], v142 offset:1024
	ds_read_b128 v[138:141], v142 offset:2048
	ds_read_b128 v[142:145], v142 offset:3072
	s_waitcnt vmcnt(6)
	s_barrier
	v_mfma_f32_16x16x32_bf16 v[54:57], v[178:181], v[146:149], v[54:57]
	v_mfma_f32_16x16x32_bf16 v[50:53], v[200:203], v[146:149], v[50:53]
	v_mfma_f32_16x16x32_bf16 v[38:41], v[178:181], v[154:157], v[38:41]
	v_mfma_f32_16x16x32_bf16 v[34:37], v[200:203], v[154:157], v[34:37]
	v_mfma_f32_16x16x32_bf16 v[22:25], v[178:181], v[162:165], v[22:25]
	v_mfma_f32_16x16x32_bf16 v[18:21], v[200:203], v[162:165], v[18:21]
	v_mfma_f32_16x16x32_bf16 v[6:9], v[178:181], v[170:173], v[6:9]
	v_mfma_f32_16x16x32_bf16 v[2:5], v[200:203], v[170:173], v[2:5]
	v_mfma_f32_16x16x32_bf16 v[54:57], v[182:185], v[150:153], v[54:57]
	v_mfma_f32_16x16x32_bf16 v[50:53], v[204:207], v[150:153], v[50:53]
	v_mfma_f32_16x16x32_bf16 v[38:41], v[182:185], v[158:161], v[38:41]
	v_mfma_f32_16x16x32_bf16 v[34:37], v[204:207], v[158:161], v[34:37]
	v_mfma_f32_16x16x32_bf16 v[22:25], v[182:185], v[166:169], v[22:25]
	v_mfma_f32_16x16x32_bf16 v[18:21], v[204:207], v[166:169], v[18:21]
	v_mfma_f32_16x16x32_bf16 v[6:9], v[182:185], v[174:177], v[6:9]
	v_mfma_f32_16x16x32_bf16 v[2:5], v[204:207], v[174:177], v[2:5]
	s_barrier
	s_add_u32 s88, s92, 0xc0000
	s_addc_u32 s89, s93, 0
	s_mov_b32 m0, s43
	ds_read_b128 v[146:149], v213 offset:32768
	ds_read_b128 v[150:153], v213 offset:33792
	ds_read_b128 v[154:157], v213 offset:34816
	ds_read_b128 v[158:161], v213 offset:35840
	ds_read_b128 v[162:165], v213 offset:36864
	ds_read_b128 v[166:169], v213 offset:37888
	ds_read_b128 v[170:173], v213 offset:38912
	ds_read_b128 v[174:177], v213 offset:39936
	global_load_lds_dwordx4 v190, s[88:89]
	s_mov_b32 m0, s44
	s_nop 0
	global_load_lds_dwordx4 v192, s[88:89]
	s_waitcnt lgkmcnt(8)
	s_barrier
	s_waitcnt lgkmcnt(0)
	v_mfma_f32_16x16x32_bf16 v[126:129], v[130:133], v[146:149], v[126:129]
	v_mfma_f32_16x16x32_bf16 v[122:125], v[138:141], v[146:149], v[122:125]
	v_mfma_f32_16x16x32_bf16 v[110:113], v[130:133], v[154:157], v[110:113]
	v_mfma_f32_16x16x32_bf16 v[106:109], v[138:141], v[154:157], v[106:109]
	v_mfma_f32_16x16x32_bf16 v[94:97], v[130:133], v[162:165], v[94:97]
	v_mfma_f32_16x16x32_bf16 v[90:93], v[138:141], v[162:165], v[90:93]
	v_mfma_f32_16x16x32_bf16 v[78:81], v[130:133], v[170:173], v[78:81]
	v_mfma_f32_16x16x32_bf16 v[74:77], v[138:141], v[170:173], v[74:77]
	v_mfma_f32_16x16x32_bf16 v[126:129], v[134:137], v[150:153], v[126:129]
	v_mfma_f32_16x16x32_bf16 v[122:125], v[142:145], v[150:153], v[122:125]
	v_mfma_f32_16x16x32_bf16 v[110:113], v[134:137], v[158:161], v[110:113]
	v_mfma_f32_16x16x32_bf16 v[106:109], v[142:145], v[158:161], v[106:109]
	v_mfma_f32_16x16x32_bf16 v[94:97], v[134:137], v[166:169], v[94:97]
	v_mfma_f32_16x16x32_bf16 v[90:93], v[142:145], v[166:169], v[90:93]
	v_mfma_f32_16x16x32_bf16 v[78:81], v[134:137], v[174:177], v[78:81]
	v_mfma_f32_16x16x32_bf16 v[74:77], v[142:145], v[174:177], v[74:77]
	s_barrier
	s_add_i32 s87, 0, 0x1c000
	s_add_i32 s79, s79, s38
	v_add_u32_e32 v204, s87, v212
	v_lshl_add_u64 v[186:187], v[186:187], 0, s[40:41]
	s_mov_b32 m0, s79
	ds_read_b128 v[178:181], v204
	ds_read_b128 v[182:185], v204 offset:1024
	ds_read_b128 v[200:203], v204 offset:2048
	ds_read_b128 v[204:207], v204 offset:3072
	global_load_lds_dwordx4 v[186:187], off
	s_add_i32 m0, s79, 0x2000
	v_lshl_add_u64 v[186:187], v[208:209], 0, s[40:41]
	global_load_lds_dwordx4 v[186:187], off
	s_barrier
	s_waitcnt lgkmcnt(0)
	v_mfma_f32_16x16x32_bf16 v[118:121], v[178:181], v[146:149], v[118:121]
	v_mfma_f32_16x16x32_bf16 v[114:117], v[200:203], v[146:149], v[114:117]
	v_mfma_f32_16x16x32_bf16 v[102:105], v[178:181], v[154:157], v[102:105]
	v_mfma_f32_16x16x32_bf16 v[98:101], v[200:203], v[154:157], v[98:101]
	v_mfma_f32_16x16x32_bf16 v[86:89], v[178:181], v[162:165], v[86:89]
	v_mfma_f32_16x16x32_bf16 v[82:85], v[200:203], v[162:165], v[82:85]
	v_mfma_f32_16x16x32_bf16 v[70:73], v[178:181], v[170:173], v[70:73]
	v_mfma_f32_16x16x32_bf16 v[66:69], v[200:203], v[170:173], v[66:69]
	v_mfma_f32_16x16x32_bf16 v[118:121], v[182:185], v[150:153], v[118:121]
	v_mfma_f32_16x16x32_bf16 v[114:117], v[204:207], v[150:153], v[114:117]
	v_mfma_f32_16x16x32_bf16 v[102:105], v[182:185], v[158:161], v[102:105]
	v_mfma_f32_16x16x32_bf16 v[98:101], v[204:207], v[158:161], v[98:101]
	v_mfma_f32_16x16x32_bf16 v[86:89], v[182:185], v[166:169], v[86:89]
	v_mfma_f32_16x16x32_bf16 v[82:85], v[204:207], v[166:169], v[82:85]
	v_mfma_f32_16x16x32_bf16 v[70:73], v[182:185], v[174:177], v[70:73]
	v_mfma_f32_16x16x32_bf16 v[66:69], v[204:207], v[174:177], v[66:69]
	s_mov_b32 m0, s60
	v_lshl_add_u64 v[186:187], v[210:211], 0, s[40:41]
	s_barrier
	ds_read_b128 v[146:149], v213 offset:49152
	ds_read_b128 v[150:153], v213 offset:50176
	ds_read_b128 v[154:157], v213 offset:51200
	ds_read_b128 v[158:161], v213 offset:52224
	ds_read_b128 v[162:165], v213 offset:53248
	ds_read_b128 v[166:169], v213 offset:54272
	ds_read_b128 v[170:173], v213 offset:55296
	ds_read_b128 v[174:177], v213 offset:56320
	global_load_lds_dwordx4 v[186:187], off
	s_mov_b32 m0, s61
	v_lshl_add_u64 v[186:187], v[214:215], 0, s[40:41]
	global_load_lds_dwordx4 v[186:187], off
	s_waitcnt vmcnt(10)
	s_barrier
	s_waitcnt lgkmcnt(0)
	v_mfma_f32_16x16x32_bf16 v[62:65], v[130:133], v[146:149], v[62:65]
	v_mfma_f32_16x16x32_bf16 v[58:61], v[138:141], v[146:149], v[58:61]
	v_mfma_f32_16x16x32_bf16 v[46:49], v[130:133], v[154:157], v[46:49]
	v_mfma_f32_16x16x32_bf16 v[42:45], v[138:141], v[154:157], v[42:45]
	v_mfma_f32_16x16x32_bf16 v[30:33], v[130:133], v[162:165], v[30:33]
	v_mfma_f32_16x16x32_bf16 v[26:29], v[138:141], v[162:165], v[26:29]
	v_mfma_f32_16x16x32_bf16 v[14:17], v[130:133], v[170:173], v[14:17]
	v_mfma_f32_16x16x32_bf16 v[10:13], v[138:141], v[170:173], v[10:13]
	v_mfma_f32_16x16x32_bf16 v[62:65], v[134:137], v[150:153], v[62:65]
	v_mfma_f32_16x16x32_bf16 v[58:61], v[142:145], v[150:153], v[58:61]
	v_mfma_f32_16x16x32_bf16 v[46:49], v[134:137], v[158:161], v[46:49]
	v_mfma_f32_16x16x32_bf16 v[42:45], v[142:145], v[158:161], v[42:45]
	v_mfma_f32_16x16x32_bf16 v[30:33], v[134:137], v[166:169], v[30:33]
	v_mfma_f32_16x16x32_bf16 v[26:29], v[142:145], v[166:169], v[26:29]
	v_mfma_f32_16x16x32_bf16 v[14:17], v[134:137], v[174:177], v[14:17]
	v_mfma_f32_16x16x32_bf16 v[10:13], v[142:145], v[174:177], v[10:13]
	s_barrier
	s_add_u32 s88, s90, 0x40080
	s_addc_u32 s89, s91, 0
	s_add_i32 s79, s87, s38
	s_mov_b32 m0, s79
	s_nop 0
	global_load_lds_dwordx4 v0, s[88:89]
	s_add_i32 m0, s79, 0x2000
	s_nop 0
	global_load_lds_dwordx4 v194, s[88:89]
	s_add_i32 s79, 0, 0x10000
	v_add_u32_e32 v142, s79, v212
	ds_read_b128 v[130:133], v142
	ds_read_b128 v[134:137], v142 offset:1024
	ds_read_b128 v[138:141], v142 offset:2048
	ds_read_b128 v[142:145], v142 offset:3072
	s_waitcnt vmcnt(6)
	s_barrier
	v_mfma_f32_16x16x32_bf16 v[54:57], v[178:181], v[146:149], v[54:57]
	v_mfma_f32_16x16x32_bf16 v[50:53], v[200:203], v[146:149], v[50:53]
	v_mfma_f32_16x16x32_bf16 v[38:41], v[178:181], v[154:157], v[38:41]
	v_mfma_f32_16x16x32_bf16 v[34:37], v[200:203], v[154:157], v[34:37]
	v_mfma_f32_16x16x32_bf16 v[22:25], v[178:181], v[162:165], v[22:25]
	v_mfma_f32_16x16x32_bf16 v[18:21], v[200:203], v[162:165], v[18:21]
	v_mfma_f32_16x16x32_bf16 v[6:9], v[178:181], v[170:173], v[6:9]
	v_mfma_f32_16x16x32_bf16 v[2:5], v[200:203], v[170:173], v[2:5]
	v_mfma_f32_16x16x32_bf16 v[54:57], v[182:185], v[150:153], v[54:57]
	v_mfma_f32_16x16x32_bf16 v[50:53], v[204:207], v[150:153], v[50:53]
	v_mfma_f32_16x16x32_bf16 v[38:41], v[182:185], v[158:161], v[38:41]
	v_mfma_f32_16x16x32_bf16 v[34:37], v[204:207], v[158:161], v[34:37]
	v_mfma_f32_16x16x32_bf16 v[22:25], v[182:185], v[166:169], v[22:25]
	v_mfma_f32_16x16x32_bf16 v[18:21], v[204:207], v[166:169], v[18:21]
	v_mfma_f32_16x16x32_bf16 v[6:9], v[182:185], v[174:177], v[6:9]
	v_mfma_f32_16x16x32_bf16 v[2:5], v[204:207], v[174:177], v[2:5]
	s_add_i32 s78, s78, 2
	s_add_u32 s34, s34, 0x100
	s_addc_u32 s75, s75, 0
	s_mov_b64 s[88:89], s[4:5]
	s_add_u32 s4, s88, 0x100
	s_addc_u32 s5, s89, 0
	s_cmp_eq_u32 s78, 12
	s_cselect_b32 s93, s17, s5
	s_cselect_b32 s92, s16, s4
	s_cselect_b32 s91, s15, s75
	s_cselect_b32 s90, s23, s34
	s_cmp_gt_u32 s78, 13
	s_barrier
	s_cbranch_scc0 .LBB0_838
	s_waitcnt lgkmcnt(0)
	s_lshl_b32 s4, s22, 8
	v_mov_b32_e32 v186, v252
	s_add_i32 s4, s4, s47
	s_nop 0
	v_and_or_b32 v202, v186, 15, s4
	s_lshl_b32 s4, s86, 8
	s_or_b32 s4, s4, s55
	v_lshrrev_b32_e32 v130, 1, v186
	v_and_or_b32 v200, v130, 24, s4
	v_ashrrev_i32_e32 v201, 31, v200
	v_ashrrev_i32_e32 v203, 31, v202
	v_lshl_add_u64 v[204:205], v[200:201], 2, s[6:7]
	v_lshlrev_b64 v[130:131], 12, v[202:203]
	v_lshl_add_u64 v[130:131], v[204:205], 0, v[130:131]
	global_load_dwordx4 v[216:219], v[130:131], off offset:16
	global_load_dwordx4 v[220:223], v[130:131], off
	global_load_dwordx4 v[178:181], v[130:131], off offset:528
	global_load_dwordx4 v[182:185], v[130:131], off offset:512
	v_or_b32_e32 v210, 16, v202
	v_ashrrev_i32_e32 v211, 31, v210
	v_lshlrev_b64 v[130:131], 12, v[210:211]
	v_or_b32_e32 v208, 32, v202
	v_lshl_add_u64 v[130:131], v[204:205], 0, v[130:131]
	v_ashrrev_i32_e32 v209, 31, v208
	global_load_dwordx4 v[170:173], v[130:131], off offset:16
	global_load_dwordx4 v[174:177], v[130:131], off
	global_load_dwordx4 v[162:165], v[130:131], off offset:528
	global_load_dwordx4 v[166:169], v[130:131], off offset:512
	v_lshlrev_b64 v[130:131], 12, v[208:209]
	v_or_b32_e32 v206, 48, v202
	v_lshl_add_u64 v[130:131], v[204:205], 0, v[130:131]
	v_ashrrev_i32_e32 v207, 31, v206
	global_load_dwordx4 v[154:157], v[130:131], off offset:16
	global_load_dwordx4 v[158:161], v[130:131], off
	global_load_dwordx4 v[138:141], v[130:131], off offset:528
	global_load_dwordx4 v[142:145], v[130:131], off offset:512
	v_lshlrev_b64 v[130:131], 12, v[206:207]
	v_lshl_add_u64 v[134:135], v[204:205], 0, v[130:131]
	global_load_dwordx4 v[146:149], v[134:135], off offset:16
	global_load_dwordx4 v[150:153], v[134:135], off
	global_load_dwordx4 v[130:133], v[134:135], off offset:528
	s_nop 0
	global_load_dwordx4 v[134:137], v[134:135], off offset:512
	v_and_b32_e32 v186, 63, v186
	v_lshlrev_b32_e32 v187, 2, v186
	v_xor_b32_e32 v215, 64, v187
	v_xor_b32_e32 v214, 0x80, v187
	v_cmp_gt_u32_e32 vcc, 16, v186
	v_lshlrev_b64 v[186:187], 10, v[202:203]
	v_lshl_add_u64 v[186:187], v[186:187], 0, v[200:201]
	s_lshl_b32 s4, s86, 2
	s_ashr_i32 s5, s4, 31
	s_waitcnt vmcnt(0)
	v_pk_add_f32 v[124:125], v[124:125], v[218:219]
	v_pk_add_f32 v[128:129], v[128:129], v[222:223]
	v_pk_add_f32 v[126:127], v[126:127], v[220:221]
	v_pk_mul_f32 v[218:219], v[128:129], v[128:129]
	v_pk_mul_f32 v[220:221], v[126:127], v[126:127]
	v_pk_add_f32 v[122:123], v[122:123], v[216:217]
	v_lshl_add_u64 v[216:217], v[186:187], 2, s[12:13]
	v_add_f32_e32 v220, v220, v221
	v_add_f32_e32 v218, v218, v219
	global_store_dwordx4 v[216:217], v[126:129], off
	global_store_dwordx4 v[216:217], v[122:125], off offset:16
	v_add_f32_e32 v222, v220, v218
	v_pk_mul_f32 v[220:221], v[122:123], v[122:123]
	v_cvt_pk_bf16_f32 v126, v126, v127
	v_cvt_pk_bf16_f32 v127, v128, v129
	v_cvt_pk_bf16_f32 v128, v122, v123
	v_cvt_pk_bf16_f32 v129, v124, v125
	v_lshl_add_u64 v[122:123], v[186:187], 1, s[8:9]
	v_pk_add_f32 v[120:121], v[120:121], v[184:185]
	v_pk_add_f32 v[118:119], v[118:119], v[182:183]
	v_pk_mul_f32 v[218:219], v[124:125], v[124:125]
	global_store_dwordx4 v[122:123], v[126:129], off
	v_pk_mul_f32 v[124:125], v[120:121], v[120:121]
	v_pk_add_f32 v[116:117], v[116:117], v[180:181]
	v_pk_mul_f32 v[126:127], v[118:119], v[118:119]
	v_pk_add_f32 v[114:115], v[114:115], v[178:179]
	v_add_f32_e32 v126, v126, v127
	v_add_f32_e32 v124, v124, v125
	v_add_f32_e32 v128, v126, v124
	v_pk_mul_f32 v[124:125], v[116:117], v[116:117]
	v_pk_mul_f32 v[126:127], v[114:115], v[114:115]
	v_add_f32_e32 v220, v220, v221
	v_add_f32_e32 v218, v218, v219
	v_add_f32_e32 v126, v126, v127
	v_add_f32_e32 v124, v124, v125
	v_add_f32_e32 v218, v220, v218
	v_add_f32_e32 v124, v126, v124
	v_add_f32_e32 v218, v222, v218
	v_add_f32_e32 v124, v128, v124
	v_add_f32_e32 v124, v218, v124
	global_store_dwordx4 v[216:217], v[118:121], off offset:512
	global_store_dwordx4 v[216:217], v[114:117], off offset:528
	s_nop 0
	v_cvt_pk_bf16_f32 v118, v118, v119
	v_cvt_pk_bf16_f32 v119, v120, v121
	v_cvt_pk_bf16_f32 v120, v114, v115
	ds_bpermute_b32 v114, v215, v124
	v_cvt_pk_bf16_f32 v121, v116, v117
	global_store_dwordx4 v[122:123], v[118:121], off offset:256
	s_waitcnt lgkmcnt(0)
	v_add_f32_e32 v114, v124, v114
	ds_bpermute_b32 v115, v214, v114
	s_and_saveexec_b64 s[22:23], vcc
	s_cbranch_execz .LBB0_841
	v_lshlrev_b64 v[116:117], 6, v[202:203]
	v_lshl_add_u64 v[116:117], s[10:11], 0, v[116:117]
	v_lshl_add_u64 v[116:117], s[4:5], 2, v[116:117]
	s_lshl_b32 s34, s45, 2
	v_lshl_add_u64 v[116:117], v[116:117], 0, s[34:35]
	s_waitcnt lgkmcnt(0)
	v_add_f32_e32 v114, v114, v115
	global_store_dword v[116:117], v114, off

.LBB0_919:
	v_lshl_add_u64 v[154:155], s[6:7], 0, v[164:165]
	s_add_i32 m0, s43, 0xc000
	ds_read_b128 v[146:149], v253
	ds_read_b128 v[150:153], v253 offset:1024
	ds_read_b128 v[168:171], v253 offset:2048
	ds_read_b128 v[172:175], v253 offset:3072
	ds_read_b128 v[176:179], v253 offset:4096
	ds_read_b128 v[180:183], v253 offset:5120
	ds_read_b128 v[184:187], v253 offset:6144
	ds_read_b128 v[190:193], v253 offset:7168
	global_load_lds_dwordx4 v[154:155], off
	s_add_i32 m0, s43, 0xe000
	v_lshl_add_u64 v[154:155], s[6:7], 0, v[166:167]
	global_load_lds_dwordx4 v[154:155], off
	s_waitcnt lgkmcnt(8)
	s_barrier
	s_waitcnt lgkmcnt(0)
	v_mfma_f32_16x16x32_bf16 v[126:129], v[130:133], v[146:149], v[126:129]
	v_mfma_f32_16x16x32_bf16 v[70:73], v[138:141], v[146:149], v[70:73]
	v_mfma_f32_16x16x32_bf16 v[122:125], v[130:133], v[168:171], v[122:125]
	v_mfma_f32_16x16x32_bf16 v[74:77], v[138:141], v[168:171], v[74:77]
	v_mfma_f32_16x16x32_bf16 v[114:117], v[130:133], v[176:179], v[114:117]
	v_mfma_f32_16x16x32_bf16 v[66:69], v[138:141], v[176:179], v[66:69]
	v_mfma_f32_16x16x32_bf16 v[110:113], v[130:133], v[184:187], v[110:113]
	v_mfma_f32_16x16x32_bf16 v[78:81], v[138:141], v[184:187], v[78:81]
	v_mfma_f32_16x16x32_bf16 v[126:129], v[134:137], v[150:153], v[126:129]
	v_mfma_f32_16x16x32_bf16 v[70:73], v[142:145], v[150:153], v[70:73]
	v_mfma_f32_16x16x32_bf16 v[122:125], v[134:137], v[172:175], v[122:125]
	v_mfma_f32_16x16x32_bf16 v[74:77], v[142:145], v[172:175], v[74:77]
	v_mfma_f32_16x16x32_bf16 v[114:117], v[134:137], v[180:183], v[114:117]
	v_mfma_f32_16x16x32_bf16 v[66:69], v[142:145], v[180:183], v[66:69]
	v_mfma_f32_16x16x32_bf16 v[110:113], v[134:137], v[190:193], v[110:113]
	v_mfma_f32_16x16x32_bf16 v[78:81], v[142:145], v[190:193], v[78:81]
	s_barrier
	s_add_i32 vcc_hi, 0, 0x14000
	s_add_i32 s6, vcc_lo, s39
	v_add_u32_e32 v0, vcc_hi, v254
	v_lshl_add_u64 v[154:155], s[90:91], 0, v[160:161]
	s_mov_b32 m0, s6
	ds_read_b128 v[194:197], v0
	ds_read_b128 v[198:201], v0 offset:1024
	ds_read_b128 v[202:205], v0 offset:2048
	ds_read_b128 v[206:209], v0 offset:3072
	global_load_lds_dwordx4 v[154:155], off
	s_add_i32 m0, s6, 0x2000
	v_lshl_add_u64 v[210:211], s[90:91], 0, v[156:157]
	global_load_lds_dwordx4 v[210:211], off
	s_barrier
	s_waitcnt lgkmcnt(0)
	v_mfma_f32_16x16x32_bf16 v[118:121], v[194:197], v[146:149], v[118:121]
	v_mfma_f32_16x16x32_bf16 v[94:97], v[202:205], v[146:149], v[94:97]
	v_mfma_f32_16x16x32_bf16 v[106:109], v[194:197], v[168:171], v[106:109]
	v_mfma_f32_16x16x32_bf16 v[90:93], v[202:205], v[168:171], v[90:93]
	v_mfma_f32_16x16x32_bf16 v[102:105], v[194:197], v[176:179], v[102:105]
	v_mfma_f32_16x16x32_bf16 v[82:85], v[202:205], v[176:179], v[82:85]
	v_mfma_f32_16x16x32_bf16 v[98:101], v[194:197], v[184:187], v[98:101]
	v_mfma_f32_16x16x32_bf16 v[86:89], v[202:205], v[184:187], v[86:89]
	v_mfma_f32_16x16x32_bf16 v[118:121], v[198:201], v[150:153], v[118:121]
	v_mfma_f32_16x16x32_bf16 v[94:97], v[206:209], v[150:153], v[94:97]
	v_mfma_f32_16x16x32_bf16 v[106:109], v[198:201], v[172:175], v[106:109]
	v_mfma_f32_16x16x32_bf16 v[90:93], v[206:209], v[172:175], v[90:93]
	v_mfma_f32_16x16x32_bf16 v[102:105], v[198:201], v[180:183], v[102:105]
	v_mfma_f32_16x16x32_bf16 v[82:85], v[206:209], v[180:183], v[82:85]
	v_mfma_f32_16x16x32_bf16 v[98:101], v[198:201], v[190:193], v[98:101]
	v_mfma_f32_16x16x32_bf16 v[86:89], v[206:209], v[190:193], v[86:89]
	s_mov_b32 m0, s43
	v_lshl_add_u64 v[212:213], s[92:93], 0, v[162:163]
	s_barrier
	ds_read_b128 v[146:149], v253 offset:16384
	ds_read_b128 v[150:153], v253 offset:17408
	ds_read_b128 v[168:171], v253 offset:18432
	ds_read_b128 v[172:175], v253 offset:19456
	ds_read_b128 v[176:179], v253 offset:20480
	ds_read_b128 v[180:183], v253 offset:21504
	ds_read_b128 v[184:187], v253 offset:22528
	ds_read_b128 v[190:193], v253 offset:23552
	global_load_lds_dwordx4 v[212:213], off
	s_mov_b32 m0, s60
	v_lshl_add_u64 v[214:215], s[92:93], 0, v[158:159]
	global_load_lds_dwordx4 v[214:215], off
	s_waitcnt vmcnt(10)
	s_barrier
	s_waitcnt lgkmcnt(0)
	v_mfma_f32_16x16x32_bf16 v[62:65], v[130:133], v[146:149], v[62:65]
	v_mfma_f32_16x16x32_bf16 v[10:13], v[138:141], v[146:149], v[10:13]
	v_mfma_f32_16x16x32_bf16 v[58:61], v[130:133], v[168:171], v[58:61]
	v_mfma_f32_16x16x32_bf16 v[14:17], v[138:141], v[168:171], v[14:17]
	v_mfma_f32_16x16x32_bf16 v[54:57], v[130:133], v[176:179], v[54:57]
	v_mfma_f32_16x16x32_bf16 v[6:9], v[138:141], v[176:179], v[6:9]
	v_mfma_f32_16x16x32_bf16 v[42:45], v[130:133], v[184:187], v[42:45]
	v_mfma_f32_16x16x32_bf16 v[2:5], v[138:141], v[184:187], v[2:5]
	v_mfma_f32_16x16x32_bf16 v[62:65], v[134:137], v[150:153], v[62:65]
	v_mfma_f32_16x16x32_bf16 v[10:13], v[142:145], v[150:153], v[10:13]
	v_mfma_f32_16x16x32_bf16 v[58:61], v[134:137], v[172:175], v[58:61]
	v_mfma_f32_16x16x32_bf16 v[14:17], v[142:145], v[172:175], v[14:17]
	v_mfma_f32_16x16x32_bf16 v[54:57], v[134:137], v[180:183], v[54:57]
	v_mfma_f32_16x16x32_bf16 v[6:9], v[142:145], v[180:183], v[6:9]
	v_mfma_f32_16x16x32_bf16 v[42:45], v[134:137], v[190:193], v[42:45]
	v_mfma_f32_16x16x32_bf16 v[2:5], v[142:145], v[190:193], v[2:5]
	s_barrier
	s_add_u32 s6, s90, 0x40000
	s_addc_u32 s7, s91, 0
	s_add_i32 vcc_lo, vcc_hi, s39
	s_mov_b32 m0, vcc_lo
	s_nop 0
	global_load_lds_dwordx4 v160, s[6:7]
	s_add_i32 m0, vcc_lo, 0x2000
	s_nop 0
	global_load_lds_dwordx4 v156, s[6:7]
	s_add_i32 vcc_lo, 0, 0x18000
	v_add_u32_e32 v0, vcc_lo, v254
	ds_read_b128 v[130:133], v0
	ds_read_b128 v[134:137], v0 offset:1024
	ds_read_b128 v[138:141], v0 offset:2048
	ds_read_b128 v[142:145], v0 offset:3072
	s_waitcnt vmcnt(6)
	s_barrier
	v_mfma_f32_16x16x32_bf16 v[50:53], v[194:197], v[146:149], v[50:53]
	v_mfma_f32_16x16x32_bf16 v[26:29], v[202:205], v[146:149], v[26:29]
	v_mfma_f32_16x16x32_bf16 v[46:49], v[194:197], v[168:171], v[46:49]
	v_mfma_f32_16x16x32_bf16 v[30:33], v[202:205], v[168:171], v[30:33]
	v_mfma_f32_16x16x32_bf16 v[38:41], v[194:197], v[176:179], v[38:41]
	v_mfma_f32_16x16x32_bf16 v[22:25], v[202:205], v[176:179], v[22:25]
	v_mfma_f32_16x16x32_bf16 v[34:37], v[194:197], v[184:187], v[34:37]
	v_mfma_f32_16x16x32_bf16 v[18:21], v[202:205], v[184:187], v[18:21]
	v_mfma_f32_16x16x32_bf16 v[50:53], v[198:201], v[150:153], v[50:53]
	v_mfma_f32_16x16x32_bf16 v[26:29], v[206:209], v[150:153], v[26:29]
	v_mfma_f32_16x16x32_bf16 v[46:49], v[198:201], v[172:175], v[46:49]
	v_mfma_f32_16x16x32_bf16 v[30:33], v[206:209], v[172:175], v[30:33]
	v_mfma_f32_16x16x32_bf16 v[38:41], v[198:201], v[180:183], v[38:41]
	v_mfma_f32_16x16x32_bf16 v[22:25], v[206:209], v[180:183], v[22:25]
	v_mfma_f32_16x16x32_bf16 v[34:37], v[198:201], v[190:193], v[34:37]
	v_mfma_f32_16x16x32_bf16 v[18:21], v[206:209], v[190:193], v[18:21]
	s_barrier
	s_add_u32 s6, s92, 0x40000
	s_addc_u32 s7, s93, 0
	s_mov_b32 m0, s61
	ds_read_b128 v[146:149], v253 offset:32768
	ds_read_b128 v[150:153], v253 offset:33792
	ds_read_b128 v[168:171], v253 offset:34816
	ds_read_b128 v[172:175], v253 offset:35840
	ds_read_b128 v[176:179], v253 offset:36864
	ds_read_b128 v[180:183], v253 offset:37888
	ds_read_b128 v[184:187], v253 offset:38912
	ds_read_b128 v[190:193], v253 offset:39936
	global_load_lds_dwordx4 v162, s[6:7]
	s_mov_b32 m0, s72
	s_nop 0
	global_load_lds_dwordx4 v158, s[6:7]
	s_waitcnt lgkmcnt(8)
	s_barrier
	s_waitcnt lgkmcnt(0)
	v_mfma_f32_16x16x32_bf16 v[126:129], v[130:133], v[146:149], v[126:129]
	v_mfma_f32_16x16x32_bf16 v[70:73], v[138:141], v[146:149], v[70:73]
	v_mfma_f32_16x16x32_bf16 v[122:125], v[130:133], v[168:171], v[122:125]
	v_mfma_f32_16x16x32_bf16 v[74:77], v[138:141], v[168:171], v[74:77]
	v_mfma_f32_16x16x32_bf16 v[114:117], v[130:133], v[176:179], v[114:117]
	v_mfma_f32_16x16x32_bf16 v[66:69], v[138:141], v[176:179], v[66:69]
	v_mfma_f32_16x16x32_bf16 v[110:113], v[130:133], v[184:187], v[110:113]
	v_mfma_f32_16x16x32_bf16 v[78:81], v[138:141], v[184:187], v[78:81]
	v_mfma_f32_16x16x32_bf16 v[126:129], v[134:137], v[150:153], v[126:129]
	v_mfma_f32_16x16x32_bf16 v[70:73], v[142:145], v[150:153], v[70:73]
	v_mfma_f32_16x16x32_bf16 v[122:125], v[134:137], v[172:175], v[122:125]
	v_mfma_f32_16x16x32_bf16 v[74:77], v[142:145], v[172:175], v[74:77]
	v_mfma_f32_16x16x32_bf16 v[114:117], v[134:137], v[180:183], v[114:117]
	v_mfma_f32_16x16x32_bf16 v[66:69], v[142:145], v[180:183], v[66:69]
	v_mfma_f32_16x16x32_bf16 v[110:113], v[134:137], v[190:193], v[110:113]
	v_mfma_f32_16x16x32_bf16 v[78:81], v[142:145], v[190:193], v[78:81]
	s_barrier
	s_add_i32 s92, 0, 0x1c000
	s_add_i32 s6, vcc_lo, s39
	v_add_u32_e32 v0, s92, v254
	v_lshl_add_u64 v[154:155], v[154:155], 0, s[40:41]
	s_mov_b32 m0, s6
	ds_read_b128 v[194:197], v0
	ds_read_b128 v[198:201], v0 offset:1024
	ds_read_b128 v[202:205], v0 offset:2048
	ds_read_b128 v[206:209], v0 offset:3072
	global_load_lds_dwordx4 v[154:155], off
	s_add_i32 m0, s6, 0x2000
	v_lshl_add_u64 v[154:155], v[210:211], 0, s[40:41]
	global_load_lds_dwordx4 v[154:155], off
	s_barrier
	s_waitcnt lgkmcnt(0)
	v_mfma_f32_16x16x32_bf16 v[118:121], v[194:197], v[146:149], v[118:121]
	v_mfma_f32_16x16x32_bf16 v[94:97], v[202:205], v[146:149], v[94:97]
	v_mfma_f32_16x16x32_bf16 v[106:109], v[194:197], v[168:171], v[106:109]
	v_mfma_f32_16x16x32_bf16 v[90:93], v[202:205], v[168:171], v[90:93]
	v_mfma_f32_16x16x32_bf16 v[102:105], v[194:197], v[176:179], v[102:105]
	v_mfma_f32_16x16x32_bf16 v[82:85], v[202:205], v[176:179], v[82:85]
	v_mfma_f32_16x16x32_bf16 v[98:101], v[194:197], v[184:187], v[98:101]
	v_mfma_f32_16x16x32_bf16 v[86:89], v[202:205], v[184:187], v[86:89]
	v_mfma_f32_16x16x32_bf16 v[118:121], v[198:201], v[150:153], v[118:121]
	v_mfma_f32_16x16x32_bf16 v[94:97], v[206:209], v[150:153], v[94:97]
	v_mfma_f32_16x16x32_bf16 v[106:109], v[198:201], v[172:175], v[106:109]
	v_mfma_f32_16x16x32_bf16 v[90:93], v[206:209], v[172:175], v[90:93]
	v_mfma_f32_16x16x32_bf16 v[102:105], v[198:201], v[180:183], v[102:105]
	v_mfma_f32_16x16x32_bf16 v[82:85], v[206:209], v[180:183], v[82:85]
	v_mfma_f32_16x16x32_bf16 v[98:101], v[198:201], v[190:193], v[98:101]
	v_mfma_f32_16x16x32_bf16 v[86:89], v[206:209], v[190:193], v[86:89]
	s_mov_b32 m0, s95
	v_lshl_add_u64 v[154:155], v[212:213], 0, s[40:41]
	s_barrier
	ds_read_b128 v[146:149], v253 offset:49152
	ds_read_b128 v[150:153], v253 offset:50176
	ds_read_b128 v[168:171], v253 offset:51200
	ds_read_b128 v[172:175], v253 offset:52224
	ds_read_b128 v[176:179], v253 offset:53248
	ds_read_b128 v[180:183], v253 offset:54272
	ds_read_b128 v[184:187], v253 offset:55296
	ds_read_b128 v[190:193], v253 offset:56320
	global_load_lds_dwordx4 v[154:155], off
	s_mov_b32 m0, s96
	v_lshl_add_u64 v[154:155], v[214:215], 0, s[40:41]
	global_load_lds_dwordx4 v[154:155], off
	s_waitcnt vmcnt(10)
	s_barrier
	s_waitcnt lgkmcnt(0)
	v_mfma_f32_16x16x32_bf16 v[62:65], v[130:133], v[146:149], v[62:65]
	v_mfma_f32_16x16x32_bf16 v[10:13], v[138:141], v[146:149], v[10:13]
	v_mfma_f32_16x16x32_bf16 v[58:61], v[130:133], v[168:171], v[58:61]
	v_mfma_f32_16x16x32_bf16 v[14:17], v[138:141], v[168:171], v[14:17]
	v_mfma_f32_16x16x32_bf16 v[54:57], v[130:133], v[176:179], v[54:57]
	v_mfma_f32_16x16x32_bf16 v[6:9], v[138:141], v[176:179], v[6:9]
	v_mfma_f32_16x16x32_bf16 v[42:45], v[130:133], v[184:187], v[42:45]
	v_mfma_f32_16x16x32_bf16 v[2:5], v[138:141], v[184:187], v[2:5]
	v_mfma_f32_16x16x32_bf16 v[62:65], v[134:137], v[150:153], v[62:65]
	v_mfma_f32_16x16x32_bf16 v[10:13], v[142:145], v[150:153], v[10:13]
	v_mfma_f32_16x16x32_bf16 v[58:61], v[134:137], v[172:175], v[58:61]
	v_mfma_f32_16x16x32_bf16 v[14:17], v[142:145], v[172:175], v[14:17]
	v_mfma_f32_16x16x32_bf16 v[54:57], v[134:137], v[180:183], v[54:57]
	v_mfma_f32_16x16x32_bf16 v[6:9], v[142:145], v[180:183], v[6:9]
	v_mfma_f32_16x16x32_bf16 v[42:45], v[134:137], v[190:193], v[42:45]
	v_mfma_f32_16x16x32_bf16 v[2:5], v[142:145], v[190:193], v[2:5]
	s_barrier
	s_add_u32 s6, s90, 0x40080
	s_addc_u32 s7, s91, 0
	s_add_i32 s90, s92, s39
	s_mov_b32 m0, s90
	s_nop 0
	global_load_lds_dwordx4 v160, s[6:7]
	s_add_i32 m0, s90, 0x2000
	s_nop 0
	global_load_lds_dwordx4 v156, s[6:7]
	s_add_i32 vcc_lo, 0, 0x10000
	v_add_u32_e32 v0, vcc_lo, v254
	ds_read_b128 v[130:133], v0
	ds_read_b128 v[134:137], v0 offset:1024
	ds_read_b128 v[138:141], v0 offset:2048
	ds_read_b128 v[142:145], v0 offset:3072
	s_waitcnt vmcnt(6)
	s_barrier
	v_mfma_f32_16x16x32_bf16 v[50:53], v[194:197], v[146:149], v[50:53]
	v_mfma_f32_16x16x32_bf16 v[26:29], v[202:205], v[146:149], v[26:29]
	v_mfma_f32_16x16x32_bf16 v[46:49], v[194:197], v[168:171], v[46:49]
	v_mfma_f32_16x16x32_bf16 v[30:33], v[202:205], v[168:171], v[30:33]
	v_mfma_f32_16x16x32_bf16 v[38:41], v[194:197], v[176:179], v[38:41]
	v_mfma_f32_16x16x32_bf16 v[22:25], v[202:205], v[176:179], v[22:25]
	v_mfma_f32_16x16x32_bf16 v[34:37], v[194:197], v[184:187], v[34:37]
	v_mfma_f32_16x16x32_bf16 v[18:21], v[202:205], v[184:187], v[18:21]
	v_mfma_f32_16x16x32_bf16 v[50:53], v[198:201], v[150:153], v[50:53]
	v_mfma_f32_16x16x32_bf16 v[26:29], v[206:209], v[150:153], v[26:29]
	v_mfma_f32_16x16x32_bf16 v[46:49], v[198:201], v[172:175], v[46:49]
	v_mfma_f32_16x16x32_bf16 v[30:33], v[206:209], v[172:175], v[30:33]
	v_mfma_f32_16x16x32_bf16 v[38:41], v[198:201], v[180:183], v[38:41]
	v_mfma_f32_16x16x32_bf16 v[22:25], v[206:209], v[180:183], v[22:25]
	v_mfma_f32_16x16x32_bf16 v[34:37], v[198:201], v[190:193], v[34:37]
	v_mfma_f32_16x16x32_bf16 v[18:21], v[206:209], v[190:193], v[18:21]
	s_add_i32 s45, s45, 2
	s_add_u32 s28, s28, 0x100
	s_addc_u32 s29, s29, 0
	s_mov_b64 s[6:7], s[88:89]
	s_add_u32 s88, s6, 0x100
	s_addc_u32 s89, s7, 0
	s_cmp_eq_u32 s45, 12
	s_cselect_b32 s93, s17, s89
	s_cselect_b32 s92, s22, s88
	s_cselect_b32 s91, s15, s29
	s_cselect_b32 s90, s23, s28
	s_cmp_gt_u32 s45, 13
	s_barrier
	s_cbranch_scc0 .LBB0_919
	s_waitcnt lgkmcnt(0)
	v_mov_b32_e32 v131, v252
	s_lshl_b32 s88, s5, 7
	v_bfe_u32 v130, v131, 4, 2
	v_and_b32_e32 v134, 15, v131
	v_lshlrev_b32_e32 v0, 4, v130
	s_ashr_i32 s89, s88, 31
	s_lshl_b32 s15, s4, 8
	v_or3_b32 v135, v0, s97, v134
	s_lshl_b64 s[4:5], s[88:89], 2
	v_lshrrev_b32_e32 v140, 1, v135
	s_add_u32 s4, s73, s4
	s_addc_u32 s5, s74, s5
	v_lshlrev_b32_e32 v0, 2, v140
	v_and_b32_e32 v144, 1, v131
	v_lshl_add_u64 v[132:133], s[4:5], 0, v[0:1]
	v_cmp_eq_u32_e32 vcc, 1, v144
	v_mov_b32_e32 v0, 0xb00
	s_movk_i32 s4, 0x5000
	v_cndmask_b32_e32 v141, 0, v0, vcc
	v_lshlrev_b32_e32 v0, 2, v141
	v_lshl_add_u64 v[132:133], v[132:133], 0, v[0:1]
	v_add_co_u32_e32 v138, vcc, s4, v132
	s_mov_b32 s4, 0xb000
	s_nop 0
	v_addc_co_u32_e32 v139, vcc, 0, v133, vcc
	global_load_dword v136, v[132:133], off
	global_load_dword v137, v[138:139], off offset:2048
	v_add_co_u32_e32 v132, vcc, s4, v132
	v_add_u32_e32 v0, s88, v141
	s_nop 0
	v_addc_co_u32_e32 v133, vcc, 0, v133, vcc
	global_load_dword v138, v[132:133], off
	v_or_b32_e32 v132, v140, v0
	v_ashrrev_i32_e32 v133, 31, v132
	v_lshl_add_u64 v[132:133], v[132:133], 2, s[12:13]
	global_load_dword v139, v[132:133], off
	v_lshl_add_u32 v152, v135, 4, s78
	v_and_b32_e32 v135, 63, v131
	v_cmp_eq_u32_e32 vcc, 0, v144
	v_or_b32_e32 v0, s97, v135
	v_lshrrev_b32_e32 v0, 1, v0
	v_and_or_b32 v131, v0, 63, s55
	v_add_u32_e32 v132, s15, v131
	v_ashrrev_i32_e32 v133, 31, v132
	v_lshlrev_b64 v[132:133], 6, v[132:133]
	v_lshl_add_u64 v[132:133], s[10:11], 0, v[132:133]
	v_lshlrev_b32_e32 v0, 5, v144
	v_lshl_add_u64 v[132:133], v[132:133], 0, v[0:1]
	global_load_dwordx4 v[148:151], v[132:133], off offset:16
	global_load_dwordx4 v[140:143], v[132:133], off
	s_waitcnt vmcnt(2)
	ds_write_b128 v152, v[136:139]
	s_waitcnt vmcnt(0)
	v_add_f32_e32 v133, v150, v151
	v_add_f32_e32 v0, v140, v141
	v_add_f32_e32 v132, v142, v143
	v_add_f32_e32 v0, v0, v132
	v_add_f32_e32 v132, v148, v149
	v_add_f32_e32 v132, v132, v133
	v_add_f32_e32 v0, v0, v132
	v_lshlrev_b32_e32 v132, 2, v135
	v_xor_b32_e32 v132, 4, v132
	ds_bpermute_b32 v132, v132, v0
	s_and_saveexec_b64 s[4:5], vcc
	s_cbranch_execz .LBB0_922
	s_waitcnt lgkmcnt(0)
	v_add_f32_e32 v0, v0, v132
	v_mov_b32_e32 v132, 0x358637bd
	v_fmamk_f32 v0, v0, 0x3a800000, v132
	s_mov_b32 s6, 0x800000
	v_mul_f32_e32 v132, 0x4b800000, v0
	v_cmp_gt_f32_e32 vcc, s6, v0
	v_lshl_add_u32 v131, v131, 2, 0
	v_add_u32_e32 v131, 0x20000, v131
	v_cndmask_b32_e32 v0, v0, v132, vcc
	v_rsq_f32_e32 v0, v0
	s_nop 0
	v_mul_f32_e32 v132, 0x45800000, v0
	v_cndmask_b32_e32 v0, v0, v132, vcc
	ds_write_b32 v131, v0

.LBB0_1090:
	v_lshl_add_u64 v[178:179], s[16:17], 0, v[196:197]
	s_add_i32 m0, s39, 0xc000
	ds_read_b128 v[146:149], v213
	ds_read_b128 v[150:153], v213 offset:1024
	ds_read_b128 v[154:157], v213 offset:2048
	ds_read_b128 v[158:161], v213 offset:3072
	ds_read_b128 v[162:165], v213 offset:4096
	ds_read_b128 v[166:169], v213 offset:5120
	ds_read_b128 v[170:173], v213 offset:6144
	ds_read_b128 v[174:177], v213 offset:7168
	global_load_lds_dwordx4 v[178:179], off
	s_add_i32 m0, s39, 0xe000
	v_lshl_add_u64 v[178:179], s[16:17], 0, v[198:199]
	global_load_lds_dwordx4 v[178:179], off
	s_waitcnt lgkmcnt(8)
	s_barrier
	s_waitcnt lgkmcnt(0)
	v_mfma_f32_16x16x32_bf16 v[126:129], v[130:133], v[146:149], v[126:129]
	v_mfma_f32_16x16x32_bf16 v[122:125], v[138:141], v[146:149], v[122:125]
	v_mfma_f32_16x16x32_bf16 v[110:113], v[130:133], v[154:157], v[110:113]
	v_mfma_f32_16x16x32_bf16 v[106:109], v[138:141], v[154:157], v[106:109]
	v_mfma_f32_16x16x32_bf16 v[94:97], v[130:133], v[162:165], v[94:97]
	v_mfma_f32_16x16x32_bf16 v[90:93], v[138:141], v[162:165], v[90:93]
	v_mfma_f32_16x16x32_bf16 v[78:81], v[130:133], v[170:173], v[78:81]
	v_mfma_f32_16x16x32_bf16 v[74:77], v[138:141], v[170:173], v[74:77]
	v_mfma_f32_16x16x32_bf16 v[126:129], v[134:137], v[150:153], v[126:129]
	v_mfma_f32_16x16x32_bf16 v[122:125], v[142:145], v[150:153], v[122:125]
	v_mfma_f32_16x16x32_bf16 v[110:113], v[134:137], v[158:161], v[110:113]
	v_mfma_f32_16x16x32_bf16 v[106:109], v[142:145], v[158:161], v[106:109]
	v_mfma_f32_16x16x32_bf16 v[94:97], v[134:137], v[166:169], v[94:97]
	v_mfma_f32_16x16x32_bf16 v[90:93], v[142:145], v[166:169], v[90:93]
	v_mfma_f32_16x16x32_bf16 v[78:81], v[134:137], v[174:177], v[78:81]
	v_mfma_f32_16x16x32_bf16 v[74:77], v[142:145], v[174:177], v[74:77]
	s_barrier
	s_add_i32 s91, 0, 0x14000
	v_add_u32_e32 v186, s91, v212
	s_add_i32 s16, s90, s38
	ds_read_b128 v[178:181], v186
	ds_read_b128 v[182:185], v186 offset:1024
	ds_read_b128 v[200:203], v186 offset:2048
	ds_read_b128 v[204:207], v186 offset:3072
	v_lshl_add_u64 v[186:187], s[86:87], 0, v[0:1]
	s_mov_b32 m0, s16
	v_lshl_add_u64 v[208:209], s[86:87], 0, v[194:195]
	global_load_lds_dwordx4 v[186:187], off
	s_add_i32 m0, s16, 0x2000
	s_nop 0
	global_load_lds_dwordx4 v[208:209], off
	s_barrier
	s_waitcnt lgkmcnt(0)
	v_mfma_f32_16x16x32_bf16 v[118:121], v[178:181], v[146:149], v[118:121]
	v_mfma_f32_16x16x32_bf16 v[114:117], v[200:203], v[146:149], v[114:117]
	v_mfma_f32_16x16x32_bf16 v[102:105], v[178:181], v[154:157], v[102:105]
	v_mfma_f32_16x16x32_bf16 v[98:101], v[200:203], v[154:157], v[98:101]
	v_mfma_f32_16x16x32_bf16 v[86:89], v[178:181], v[162:165], v[86:89]
	v_mfma_f32_16x16x32_bf16 v[82:85], v[200:203], v[162:165], v[82:85]
	v_mfma_f32_16x16x32_bf16 v[70:73], v[178:181], v[170:173], v[70:73]
	v_mfma_f32_16x16x32_bf16 v[66:69], v[200:203], v[170:173], v[66:69]
	v_mfma_f32_16x16x32_bf16 v[118:121], v[182:185], v[150:153], v[118:121]
	v_mfma_f32_16x16x32_bf16 v[114:117], v[204:207], v[150:153], v[114:117]
	v_mfma_f32_16x16x32_bf16 v[102:105], v[182:185], v[158:161], v[102:105]
	v_mfma_f32_16x16x32_bf16 v[98:101], v[204:207], v[158:161], v[98:101]
	v_mfma_f32_16x16x32_bf16 v[86:89], v[182:185], v[166:169], v[86:89]
	v_mfma_f32_16x16x32_bf16 v[82:85], v[204:207], v[166:169], v[82:85]
	v_mfma_f32_16x16x32_bf16 v[70:73], v[182:185], v[174:177], v[70:73]
	v_mfma_f32_16x16x32_bf16 v[66:69], v[204:207], v[174:177], v[66:69]
	s_mov_b32 m0, s39
	v_lshl_add_u64 v[210:211], s[88:89], 0, v[190:191]
	s_barrier
	ds_read_b128 v[146:149], v213 offset:16384
	ds_read_b128 v[150:153], v213 offset:17408
	ds_read_b128 v[154:157], v213 offset:18432
	ds_read_b128 v[158:161], v213 offset:19456
	ds_read_b128 v[162:165], v213 offset:20480
	ds_read_b128 v[166:169], v213 offset:21504
	ds_read_b128 v[170:173], v213 offset:22528
	ds_read_b128 v[174:177], v213 offset:23552
	global_load_lds_dwordx4 v[210:211], off
	s_mov_b32 m0, s42
	v_lshl_add_u64 v[214:215], s[88:89], 0, v[192:193]
	global_load_lds_dwordx4 v[214:215], off
	s_waitcnt vmcnt(10)
	s_barrier
	s_waitcnt lgkmcnt(0)
	v_mfma_f32_16x16x32_bf16 v[62:65], v[130:133], v[146:149], v[62:65]
	v_mfma_f32_16x16x32_bf16 v[58:61], v[138:141], v[146:149], v[58:61]
	v_mfma_f32_16x16x32_bf16 v[46:49], v[130:133], v[154:157], v[46:49]
	v_mfma_f32_16x16x32_bf16 v[42:45], v[138:141], v[154:157], v[42:45]
	v_mfma_f32_16x16x32_bf16 v[30:33], v[130:133], v[162:165], v[30:33]
	v_mfma_f32_16x16x32_bf16 v[26:29], v[138:141], v[162:165], v[26:29]
	v_mfma_f32_16x16x32_bf16 v[14:17], v[130:133], v[170:173], v[14:17]
	v_mfma_f32_16x16x32_bf16 v[10:13], v[138:141], v[170:173], v[10:13]
	v_mfma_f32_16x16x32_bf16 v[62:65], v[134:137], v[150:153], v[62:65]
	v_mfma_f32_16x16x32_bf16 v[58:61], v[142:145], v[150:153], v[58:61]
	v_mfma_f32_16x16x32_bf16 v[46:49], v[134:137], v[158:161], v[46:49]
	v_mfma_f32_16x16x32_bf16 v[42:45], v[142:145], v[158:161], v[42:45]
	v_mfma_f32_16x16x32_bf16 v[30:33], v[134:137], v[166:169], v[30:33]
	v_mfma_f32_16x16x32_bf16 v[26:29], v[142:145], v[166:169], v[26:29]
	v_mfma_f32_16x16x32_bf16 v[14:17], v[134:137], v[174:177], v[14:17]
	v_mfma_f32_16x16x32_bf16 v[10:13], v[142:145], v[174:177], v[10:13]
	s_barrier
	s_add_u32 s16, s86, 0xb0000
	s_addc_u32 s17, s87, 0
	s_add_i32 s90, s91, s38
	s_mov_b32 m0, s90
	s_nop 0
	global_load_lds_dwordx4 v0, s[16:17]
	s_add_i32 m0, s90, 0x2000
	s_nop 0
	global_load_lds_dwordx4 v194, s[16:17]
	s_add_i32 s90, 0, 0x18000
	v_add_u32_e32 v142, s90, v212
	ds_read_b128 v[130:133], v142
	ds_read_b128 v[134:137], v142 offset:1024
	ds_read_b128 v[138:141], v142 offset:2048
	ds_read_b128 v[142:145], v142 offset:3072
	s_waitcnt vmcnt(6)
	s_barrier
	v_mfma_f32_16x16x32_bf16 v[54:57], v[178:181], v[146:149], v[54:57]
	v_mfma_f32_16x16x32_bf16 v[50:53], v[200:203], v[146:149], v[50:53]
	v_mfma_f32_16x16x32_bf16 v[38:41], v[178:181], v[154:157], v[38:41]
	v_mfma_f32_16x16x32_bf16 v[34:37], v[200:203], v[154:157], v[34:37]
	v_mfma_f32_16x16x32_bf16 v[22:25], v[178:181], v[162:165], v[22:25]
	v_mfma_f32_16x16x32_bf16 v[18:21], v[200:203], v[162:165], v[18:21]
	v_mfma_f32_16x16x32_bf16 v[6:9], v[178:181], v[170:173], v[6:9]
	v_mfma_f32_16x16x32_bf16 v[2:5], v[200:203], v[170:173], v[2:5]
	v_mfma_f32_16x16x32_bf16 v[54:57], v[182:185], v[150:153], v[54:57]
	v_mfma_f32_16x16x32_bf16 v[50:53], v[204:207], v[150:153], v[50:53]
	v_mfma_f32_16x16x32_bf16 v[38:41], v[182:185], v[158:161], v[38:41]
	v_mfma_f32_16x16x32_bf16 v[34:37], v[204:207], v[158:161], v[34:37]
	v_mfma_f32_16x16x32_bf16 v[22:25], v[182:185], v[166:169], v[22:25]
	v_mfma_f32_16x16x32_bf16 v[18:21], v[204:207], v[166:169], v[18:21]
	v_mfma_f32_16x16x32_bf16 v[6:9], v[182:185], v[174:177], v[6:9]
	v_mfma_f32_16x16x32_bf16 v[2:5], v[204:207], v[174:177], v[2:5]
	s_barrier
	s_add_u32 s16, s88, 0xb0000
	s_addc_u32 s17, s89, 0
	s_mov_b32 m0, s43
	ds_read_b128 v[146:149], v213 offset:32768
	ds_read_b128 v[150:153], v213 offset:33792
	ds_read_b128 v[154:157], v213 offset:34816
	ds_read_b128 v[158:161], v213 offset:35840
	ds_read_b128 v[162:165], v213 offset:36864
	ds_read_b128 v[166:169], v213 offset:37888
	ds_read_b128 v[170:173], v213 offset:38912
	ds_read_b128 v[174:177], v213 offset:39936
	global_load_lds_dwordx4 v190, s[16:17]
	s_mov_b32 m0, s44
	s_nop 0
	global_load_lds_dwordx4 v192, s[16:17]
	s_waitcnt lgkmcnt(8)
	s_barrier
	s_waitcnt lgkmcnt(0)
	v_mfma_f32_16x16x32_bf16 v[126:129], v[130:133], v[146:149], v[126:129]
	v_mfma_f32_16x16x32_bf16 v[122:125], v[138:141], v[146:149], v[122:125]
	v_mfma_f32_16x16x32_bf16 v[110:113], v[130:133], v[154:157], v[110:113]
	v_mfma_f32_16x16x32_bf16 v[106:109], v[138:141], v[154:157], v[106:109]
	v_mfma_f32_16x16x32_bf16 v[94:97], v[130:133], v[162:165], v[94:97]
	v_mfma_f32_16x16x32_bf16 v[90:93], v[138:141], v[162:165], v[90:93]
	v_mfma_f32_16x16x32_bf16 v[78:81], v[130:133], v[170:173], v[78:81]
	v_mfma_f32_16x16x32_bf16 v[74:77], v[138:141], v[170:173], v[74:77]
	v_mfma_f32_16x16x32_bf16 v[126:129], v[134:137], v[150:153], v[126:129]
	v_mfma_f32_16x16x32_bf16 v[122:125], v[142:145], v[150:153], v[122:125]
	v_mfma_f32_16x16x32_bf16 v[110:113], v[134:137], v[158:161], v[110:113]
	v_mfma_f32_16x16x32_bf16 v[106:109], v[142:145], v[158:161], v[106:109]
	v_mfma_f32_16x16x32_bf16 v[94:97], v[134:137], v[166:169], v[94:97]
	v_mfma_f32_16x16x32_bf16 v[90:93], v[142:145], v[166:169], v[90:93]
	v_mfma_f32_16x16x32_bf16 v[78:81], v[134:137], v[174:177], v[78:81]
	v_mfma_f32_16x16x32_bf16 v[74:77], v[142:145], v[174:177], v[74:77]
	s_barrier
	s_add_i32 s88, 0, 0x1c000
	s_add_i32 s16, s90, s38
	v_add_u32_e32 v204, s88, v212
	v_lshl_add_u64 v[186:187], v[186:187], 0, s[40:41]
	s_mov_b32 m0, s16
	ds_read_b128 v[178:181], v204
	ds_read_b128 v[182:185], v204 offset:1024
	ds_read_b128 v[200:203], v204 offset:2048
	ds_read_b128 v[204:207], v204 offset:3072
	global_load_lds_dwordx4 v[186:187], off
	s_add_i32 m0, s16, 0x2000
	v_lshl_add_u64 v[186:187], v[208:209], 0, s[40:41]
	global_load_lds_dwordx4 v[186:187], off
	s_barrier
	s_waitcnt lgkmcnt(0)
	v_mfma_f32_16x16x32_bf16 v[118:121], v[178:181], v[146:149], v[118:121]
	v_mfma_f32_16x16x32_bf16 v[114:117], v[200:203], v[146:149], v[114:117]
	v_mfma_f32_16x16x32_bf16 v[102:105], v[178:181], v[154:157], v[102:105]
	v_mfma_f32_16x16x32_bf16 v[98:101], v[200:203], v[154:157], v[98:101]
	v_mfma_f32_16x16x32_bf16 v[86:89], v[178:181], v[162:165], v[86:89]
	v_mfma_f32_16x16x32_bf16 v[82:85], v[200:203], v[162:165], v[82:85]
	v_mfma_f32_16x16x32_bf16 v[70:73], v[178:181], v[170:173], v[70:73]
	v_mfma_f32_16x16x32_bf16 v[66:69], v[200:203], v[170:173], v[66:69]
	v_mfma_f32_16x16x32_bf16 v[118:121], v[182:185], v[150:153], v[118:121]
	v_mfma_f32_16x16x32_bf16 v[114:117], v[204:207], v[150:153], v[114:117]
	v_mfma_f32_16x16x32_bf16 v[102:105], v[182:185], v[158:161], v[102:105]
	v_mfma_f32_16x16x32_bf16 v[98:101], v[204:207], v[158:161], v[98:101]
	v_mfma_f32_16x16x32_bf16 v[86:89], v[182:185], v[166:169], v[86:89]
	v_mfma_f32_16x16x32_bf16 v[82:85], v[204:207], v[166:169], v[82:85]
	v_mfma_f32_16x16x32_bf16 v[70:73], v[182:185], v[174:177], v[70:73]
	v_mfma_f32_16x16x32_bf16 v[66:69], v[204:207], v[174:177], v[66:69]
	s_mov_b32 m0, s60
	v_lshl_add_u64 v[186:187], v[210:211], 0, s[40:41]
	s_barrier
	ds_read_b128 v[146:149], v213 offset:49152
	ds_read_b128 v[150:153], v213 offset:50176
	ds_read_b128 v[154:157], v213 offset:51200
	ds_read_b128 v[158:161], v213 offset:52224
	ds_read_b128 v[162:165], v213 offset:53248
	ds_read_b128 v[166:169], v213 offset:54272
	ds_read_b128 v[170:173], v213 offset:55296
	ds_read_b128 v[174:177], v213 offset:56320
	global_load_lds_dwordx4 v[186:187], off
	s_mov_b32 m0, s61
	v_lshl_add_u64 v[186:187], v[214:215], 0, s[40:41]
	global_load_lds_dwordx4 v[186:187], off
	s_waitcnt vmcnt(10)
	s_barrier
	s_waitcnt lgkmcnt(0)
	v_mfma_f32_16x16x32_bf16 v[62:65], v[130:133], v[146:149], v[62:65]
	v_mfma_f32_16x16x32_bf16 v[58:61], v[138:141], v[146:149], v[58:61]
	v_mfma_f32_16x16x32_bf16 v[46:49], v[130:133], v[154:157], v[46:49]
	v_mfma_f32_16x16x32_bf16 v[42:45], v[138:141], v[154:157], v[42:45]
	v_mfma_f32_16x16x32_bf16 v[30:33], v[130:133], v[162:165], v[30:33]
	v_mfma_f32_16x16x32_bf16 v[26:29], v[138:141], v[162:165], v[26:29]
	v_mfma_f32_16x16x32_bf16 v[14:17], v[130:133], v[170:173], v[14:17]
	v_mfma_f32_16x16x32_bf16 v[10:13], v[138:141], v[170:173], v[10:13]
	v_mfma_f32_16x16x32_bf16 v[62:65], v[134:137], v[150:153], v[62:65]
	v_mfma_f32_16x16x32_bf16 v[58:61], v[142:145], v[150:153], v[58:61]
	v_mfma_f32_16x16x32_bf16 v[46:49], v[134:137], v[158:161], v[46:49]
	v_mfma_f32_16x16x32_bf16 v[42:45], v[142:145], v[158:161], v[42:45]
	v_mfma_f32_16x16x32_bf16 v[30:33], v[134:137], v[166:169], v[30:33]
	v_mfma_f32_16x16x32_bf16 v[26:29], v[142:145], v[166:169], v[26:29]
	v_mfma_f32_16x16x32_bf16 v[14:17], v[134:137], v[174:177], v[14:17]
	v_mfma_f32_16x16x32_bf16 v[10:13], v[142:145], v[174:177], v[10:13]
	s_barrier
	s_add_u32 s16, s86, 0xb0080
	s_addc_u32 s17, s87, 0
	s_add_i32 s86, s88, s38
	s_mov_b32 m0, s86
	s_nop 0
	global_load_lds_dwordx4 v0, s[16:17]
	s_add_i32 m0, s86, 0x2000
	s_nop 0
	global_load_lds_dwordx4 v194, s[16:17]
	s_add_i32 s90, 0, 0x10000
	v_add_u32_e32 v142, s90, v212
	ds_read_b128 v[130:133], v142
	ds_read_b128 v[134:137], v142 offset:1024
	ds_read_b128 v[138:141], v142 offset:2048
	ds_read_b128 v[142:145], v142 offset:3072
	s_waitcnt vmcnt(6)
	s_barrier
	v_mfma_f32_16x16x32_bf16 v[54:57], v[178:181], v[146:149], v[54:57]
	v_mfma_f32_16x16x32_bf16 v[50:53], v[200:203], v[146:149], v[50:53]
	v_mfma_f32_16x16x32_bf16 v[38:41], v[178:181], v[154:157], v[38:41]
	v_mfma_f32_16x16x32_bf16 v[34:37], v[200:203], v[154:157], v[34:37]
	v_mfma_f32_16x16x32_bf16 v[22:25], v[178:181], v[162:165], v[22:25]
	v_mfma_f32_16x16x32_bf16 v[18:21], v[200:203], v[162:165], v[18:21]
	v_mfma_f32_16x16x32_bf16 v[6:9], v[178:181], v[170:173], v[6:9]
	v_mfma_f32_16x16x32_bf16 v[2:5], v[200:203], v[170:173], v[2:5]
	v_mfma_f32_16x16x32_bf16 v[54:57], v[182:185], v[150:153], v[54:57]
	v_mfma_f32_16x16x32_bf16 v[50:53], v[204:207], v[150:153], v[50:53]
	v_mfma_f32_16x16x32_bf16 v[38:41], v[182:185], v[158:161], v[38:41]
	v_mfma_f32_16x16x32_bf16 v[34:37], v[204:207], v[158:161], v[34:37]
	v_mfma_f32_16x16x32_bf16 v[22:25], v[182:185], v[166:169], v[22:25]
	v_mfma_f32_16x16x32_bf16 v[18:21], v[204:207], v[166:169], v[18:21]
	v_mfma_f32_16x16x32_bf16 v[6:9], v[182:185], v[174:177], v[6:9]
	v_mfma_f32_16x16x32_bf16 v[2:5], v[204:207], v[174:177], v[2:5]
	s_add_i32 s79, s79, 2
	s_add_u32 s34, s34, 0x100
	s_addc_u32 s78, s78, 0
	s_mov_b64 s[16:17], s[84:85]
	s_add_u32 s84, s16, 0x100
	s_addc_u32 s85, s17, 0
	s_cmp_eq_u32 s79, 40
	s_cselect_b32 s89, s5, s85
	s_cselect_b32 s88, s4, s84
	s_cselect_b32 s87, s7, s78
	s_cselect_b32 s86, s6, s34
	s_cmp_gt_u32 s79, 41
	s_barrier
	s_cbranch_scc0 .LBB0_1090
	s_waitcnt lgkmcnt(0)
	s_lshl_b32 s16, s23, 8
	v_mov_b32_e32 v186, v252
	s_add_i32 s16, s16, s47
	s_nop 0
	v_and_or_b32 v202, v186, 15, s16
	s_lshl_b32 s16, s22, 8
	s_or_b32 s16, s16, s55
	v_lshrrev_b32_e32 v130, 1, v186
	v_and_or_b32 v200, v130, 24, s16
	v_ashrrev_i32_e32 v201, 31, v200
	v_ashrrev_i32_e32 v203, 31, v202
	v_lshl_add_u64 v[204:205], v[200:201], 2, s[12:13]
	v_lshlrev_b64 v[130:131], 12, v[202:203]
	v_lshl_add_u64 v[130:131], v[204:205], 0, v[130:131]
	global_load_dwordx4 v[216:219], v[130:131], off offset:16
	global_load_dwordx4 v[220:223], v[130:131], off
	global_load_dwordx4 v[178:181], v[130:131], off offset:528
	global_load_dwordx4 v[182:185], v[130:131], off offset:512
	v_or_b32_e32 v210, 16, v202
	v_ashrrev_i32_e32 v211, 31, v210
	v_lshlrev_b64 v[130:131], 12, v[210:211]
	v_or_b32_e32 v208, 32, v202
	v_lshl_add_u64 v[130:131], v[204:205], 0, v[130:131]
	v_ashrrev_i32_e32 v209, 31, v208
	global_load_dwordx4 v[170:173], v[130:131], off offset:16
	global_load_dwordx4 v[174:177], v[130:131], off
	global_load_dwordx4 v[162:165], v[130:131], off offset:528
	global_load_dwordx4 v[166:169], v[130:131], off offset:512
	v_lshlrev_b64 v[130:131], 12, v[208:209]
	v_or_b32_e32 v206, 48, v202
	v_lshl_add_u64 v[130:131], v[204:205], 0, v[130:131]
	v_ashrrev_i32_e32 v207, 31, v206
	global_load_dwordx4 v[154:157], v[130:131], off offset:16
	global_load_dwordx4 v[158:161], v[130:131], off
	global_load_dwordx4 v[138:141], v[130:131], off offset:528
	global_load_dwordx4 v[142:145], v[130:131], off offset:512
	v_lshlrev_b64 v[130:131], 12, v[206:207]
	v_lshl_add_u64 v[134:135], v[204:205], 0, v[130:131]
	global_load_dwordx4 v[146:149], v[134:135], off offset:16
	global_load_dwordx4 v[150:153], v[134:135], off
	global_load_dwordx4 v[130:133], v[134:135], off offset:528
	s_nop 0
	global_load_dwordx4 v[134:137], v[134:135], off offset:512
	v_and_b32_e32 v186, 63, v186
	v_lshlrev_b32_e32 v187, 2, v186
	v_xor_b32_e32 v215, 64, v187
	v_xor_b32_e32 v214, 0x80, v187
	v_cmp_gt_u32_e32 vcc, 16, v186
	v_lshlrev_b64 v[186:187], 10, v[202:203]
	v_lshl_add_u64 v[186:187], v[186:187], 0, v[200:201]
	s_lshl_b32 s16, s22, 2
	s_ashr_i32 s17, s16, 31
	s_waitcnt vmcnt(0)
	v_pk_add_f32 v[124:125], v[124:125], v[218:219]
	v_pk_add_f32 v[128:129], v[128:129], v[222:223]
	v_pk_add_f32 v[126:127], v[126:127], v[220:221]
	v_pk_mul_f32 v[218:219], v[128:129], v[128:129]
	v_pk_mul_f32 v[220:221], v[126:127], v[126:127]
	v_pk_add_f32 v[122:123], v[122:123], v[216:217]
	v_lshl_add_u64 v[216:217], v[186:187], 2, s[14:15]
	v_add_f32_e32 v220, v220, v221
	v_add_f32_e32 v218, v218, v219
	global_store_dwordx4 v[216:217], v[126:129], off
	global_store_dwordx4 v[216:217], v[122:125], off offset:16
	v_add_f32_e32 v222, v220, v218
	v_pk_mul_f32 v[220:221], v[122:123], v[122:123]
	v_cvt_pk_bf16_f32 v126, v126, v127
	v_cvt_pk_bf16_f32 v127, v128, v129
	v_cvt_pk_bf16_f32 v128, v122, v123
	v_cvt_pk_bf16_f32 v129, v124, v125
	v_lshl_add_u64 v[122:123], v[186:187], 1, s[80:81]
	v_pk_add_f32 v[120:121], v[120:121], v[184:185]
	v_pk_add_f32 v[118:119], v[118:119], v[182:183]
	v_pk_mul_f32 v[218:219], v[124:125], v[124:125]
	global_store_dwordx4 v[122:123], v[126:129], off
	v_pk_mul_f32 v[124:125], v[120:121], v[120:121]
	v_pk_add_f32 v[116:117], v[116:117], v[180:181]
	v_pk_mul_f32 v[126:127], v[118:119], v[118:119]
	v_pk_add_f32 v[114:115], v[114:115], v[178:179]
	v_add_f32_e32 v126, v126, v127
	v_add_f32_e32 v124, v124, v125
	v_add_f32_e32 v128, v126, v124
	v_pk_mul_f32 v[124:125], v[116:117], v[116:117]
	v_pk_mul_f32 v[126:127], v[114:115], v[114:115]
	v_add_f32_e32 v220, v220, v221
	v_add_f32_e32 v218, v218, v219
	v_add_f32_e32 v126, v126, v127
	v_add_f32_e32 v124, v124, v125
	v_add_f32_e32 v218, v220, v218
	v_add_f32_e32 v124, v126, v124
	v_add_f32_e32 v218, v222, v218
	v_add_f32_e32 v124, v128, v124
	v_add_f32_e32 v124, v218, v124
	global_store_dwordx4 v[216:217], v[118:121], off offset:512
	global_store_dwordx4 v[216:217], v[114:117], off offset:528
	s_nop 0
	v_cvt_pk_bf16_f32 v118, v118, v119
	v_cvt_pk_bf16_f32 v119, v120, v121
	v_cvt_pk_bf16_f32 v120, v114, v115
	ds_bpermute_b32 v114, v215, v124
	v_cvt_pk_bf16_f32 v121, v116, v117
	global_store_dwordx4 v[122:123], v[118:121], off offset:256
	s_waitcnt lgkmcnt(0)
	v_add_f32_e32 v114, v124, v114
	ds_bpermute_b32 v115, v214, v114
	s_and_saveexec_b64 s[22:23], vcc
	s_cbranch_execz .LBB0_1093
	v_lshlrev_b64 v[116:117], 6, v[202:203]
	v_lshl_add_u64 v[116:117], s[82:83], 0, v[116:117]
	v_lshl_add_u64 v[116:117], s[16:17], 2, v[116:117]
	s_lshl_b32 s34, s45, 2
	v_lshl_add_u64 v[116:117], v[116:117], 0, s[34:35]
	s_waitcnt lgkmcnt(0)
	v_add_f32_e32 v114, v114, v115
	global_store_dword v[116:117], v114, off

.LBB0_1209:
	s_waitcnt lgkmcnt(0)
	s_add_i32 m0, s39, 0xc000
	ds_read_b128 v[158:161], v171
	ds_read_b128 v[162:165], v171 offset:1024
	ds_read_b128 v[166:169], v171 offset:2048
	ds_read_b128 v[172:175], v171 offset:3072
	ds_read_b128 v[176:179], v171 offset:4096
	ds_read_b128 v[180:183], v171 offset:5120
	ds_read_b128 v[184:187], v171 offset:6144
	ds_read_b128 v[190:193], v171 offset:7168
	global_load_lds_dwordx4 v154, s[88:89]
	s_add_i32 m0, s39, 0xe000
	s_nop 0
	global_load_lds_dwordx4 v156, s[88:89]
	s_waitcnt lgkmcnt(8)
	s_barrier
	s_waitcnt lgkmcnt(0)
	v_mfma_f32_16x16x32_bf16 v[126:129], v[130:133], v[158:161], v[126:129]
	v_mfma_f32_16x16x32_bf16 v[122:125], v[138:141], v[158:161], v[122:125]
	v_mfma_f32_16x16x32_bf16 v[110:113], v[130:133], v[166:169], v[110:113]
	v_mfma_f32_16x16x32_bf16 v[106:109], v[138:141], v[166:169], v[106:109]
	v_mfma_f32_16x16x32_bf16 v[94:97], v[130:133], v[176:179], v[94:97]
	v_mfma_f32_16x16x32_bf16 v[90:93], v[138:141], v[176:179], v[90:93]
	v_mfma_f32_16x16x32_bf16 v[78:81], v[130:133], v[184:187], v[78:81]
	v_mfma_f32_16x16x32_bf16 v[74:77], v[138:141], v[184:187], v[74:77]
	v_mfma_f32_16x16x32_bf16 v[126:129], v[134:137], v[162:165], v[126:129]
	v_mfma_f32_16x16x32_bf16 v[122:125], v[142:145], v[162:165], v[122:125]
	v_mfma_f32_16x16x32_bf16 v[110:113], v[134:137], v[172:175], v[110:113]
	v_mfma_f32_16x16x32_bf16 v[106:109], v[142:145], v[172:175], v[106:109]
	v_mfma_f32_16x16x32_bf16 v[94:97], v[134:137], v[180:183], v[94:97]
	v_mfma_f32_16x16x32_bf16 v[90:93], v[142:145], v[180:183], v[90:93]
	v_mfma_f32_16x16x32_bf16 v[78:81], v[134:137], v[190:193], v[78:81]
	v_mfma_f32_16x16x32_bf16 v[74:77], v[142:145], v[190:193], v[74:77]
	s_barrier
	s_add_i32 s87, 0, 0x14000
	s_add_i32 s94, s94, s38
	v_add_u32_e32 v0, s87, v170
	v_lshl_add_u64 v[210:211], s[90:91], 0, v[148:149]
	s_mov_b32 m0, s94
	ds_read_b128 v[194:197], v0
	ds_read_b128 v[198:201], v0 offset:1024
	ds_read_b128 v[202:205], v0 offset:2048
	ds_read_b128 v[206:209], v0 offset:3072
	global_load_lds_dwordx4 v[210:211], off
	s_add_i32 m0, s94, 0x2000
	v_lshl_add_u64 v[212:213], s[90:91], 0, v[152:153]
	global_load_lds_dwordx4 v[212:213], off
	s_barrier
	s_waitcnt lgkmcnt(0)
	v_mfma_f32_16x16x32_bf16 v[118:121], v[194:197], v[158:161], v[118:121]
	v_mfma_f32_16x16x32_bf16 v[114:117], v[202:205], v[158:161], v[114:117]
	v_mfma_f32_16x16x32_bf16 v[102:105], v[194:197], v[166:169], v[102:105]
	v_mfma_f32_16x16x32_bf16 v[98:101], v[202:205], v[166:169], v[98:101]
	v_mfma_f32_16x16x32_bf16 v[86:89], v[194:197], v[176:179], v[86:89]
	v_mfma_f32_16x16x32_bf16 v[82:85], v[202:205], v[176:179], v[82:85]
	v_mfma_f32_16x16x32_bf16 v[70:73], v[194:197], v[184:187], v[70:73]
	v_mfma_f32_16x16x32_bf16 v[66:69], v[202:205], v[184:187], v[66:69]
	v_mfma_f32_16x16x32_bf16 v[118:121], v[198:201], v[162:165], v[118:121]
	v_mfma_f32_16x16x32_bf16 v[114:117], v[206:209], v[162:165], v[114:117]
	v_mfma_f32_16x16x32_bf16 v[102:105], v[198:201], v[172:175], v[102:105]
	v_mfma_f32_16x16x32_bf16 v[98:101], v[206:209], v[172:175], v[98:101]
	v_mfma_f32_16x16x32_bf16 v[86:89], v[198:201], v[180:183], v[86:89]
	v_mfma_f32_16x16x32_bf16 v[82:85], v[206:209], v[180:183], v[82:85]
	v_mfma_f32_16x16x32_bf16 v[70:73], v[198:201], v[190:193], v[70:73]
	v_mfma_f32_16x16x32_bf16 v[66:69], v[206:209], v[190:193], v[66:69]
	s_mov_b32 m0, s39
	v_lshl_add_u64 v[214:215], s[92:93], 0, v[146:147]
	s_barrier
	ds_read_b128 v[158:161], v171 offset:16384
	ds_read_b128 v[162:165], v171 offset:17408
	ds_read_b128 v[166:169], v171 offset:18432
	ds_read_b128 v[172:175], v171 offset:19456
	ds_read_b128 v[176:179], v171 offset:20480
	ds_read_b128 v[180:183], v171 offset:21504
	ds_read_b128 v[184:187], v171 offset:22528
	ds_read_b128 v[190:193], v171 offset:23552
	global_load_lds_dwordx4 v[214:215], off
	s_mov_b32 m0, s42
	v_lshl_add_u64 v[216:217], s[92:93], 0, v[150:151]
	global_load_lds_dwordx4 v[216:217], off
	s_waitcnt vmcnt(10)
	s_barrier
	s_waitcnt lgkmcnt(0)
	v_mfma_f32_16x16x32_bf16 v[62:65], v[130:133], v[158:161], v[62:65]
	v_mfma_f32_16x16x32_bf16 v[58:61], v[138:141], v[158:161], v[58:61]
	v_mfma_f32_16x16x32_bf16 v[46:49], v[130:133], v[166:169], v[46:49]
	v_mfma_f32_16x16x32_bf16 v[42:45], v[138:141], v[166:169], v[42:45]
	v_mfma_f32_16x16x32_bf16 v[30:33], v[130:133], v[176:179], v[30:33]
	v_mfma_f32_16x16x32_bf16 v[26:29], v[138:141], v[176:179], v[26:29]
	v_mfma_f32_16x16x32_bf16 v[14:17], v[130:133], v[184:187], v[14:17]
	v_mfma_f32_16x16x32_bf16 v[10:13], v[138:141], v[184:187], v[10:13]
	v_mfma_f32_16x16x32_bf16 v[62:65], v[134:137], v[162:165], v[62:65]
	v_mfma_f32_16x16x32_bf16 v[58:61], v[142:145], v[162:165], v[58:61]
	v_mfma_f32_16x16x32_bf16 v[46:49], v[134:137], v[172:175], v[46:49]
	v_mfma_f32_16x16x32_bf16 v[42:45], v[142:145], v[172:175], v[42:45]
	v_mfma_f32_16x16x32_bf16 v[30:33], v[134:137], v[180:183], v[30:33]
	v_mfma_f32_16x16x32_bf16 v[26:29], v[142:145], v[180:183], v[26:29]
	v_mfma_f32_16x16x32_bf16 v[14:17], v[134:137], v[190:193], v[14:17]
	v_mfma_f32_16x16x32_bf16 v[10:13], v[142:145], v[190:193], v[10:13]
	s_barrier
	s_add_u32 s94, s90, 0x40000
	s_addc_u32 s95, s91, 0
	s_add_i32 s87, s87, s38
	s_mov_b32 m0, s87
	s_nop 0
	global_load_lds_dwordx4 v148, s[94:95]
	s_add_i32 m0, s87, 0x2000
	s_nop 0
	global_load_lds_dwordx4 v152, s[94:95]
	s_add_i32 s87, 0, 0x18000
	v_add_u32_e32 v0, s87, v170
	ds_read_b128 v[130:133], v0
	ds_read_b128 v[134:137], v0 offset:1024
	ds_read_b128 v[138:141], v0 offset:2048
	ds_read_b128 v[142:145], v0 offset:3072
	s_waitcnt vmcnt(6)
	s_barrier
	v_mfma_f32_16x16x32_bf16 v[54:57], v[194:197], v[158:161], v[54:57]
	v_mfma_f32_16x16x32_bf16 v[50:53], v[202:205], v[158:161], v[50:53]
	v_mfma_f32_16x16x32_bf16 v[38:41], v[194:197], v[166:169], v[38:41]
	v_mfma_f32_16x16x32_bf16 v[34:37], v[202:205], v[166:169], v[34:37]
	v_mfma_f32_16x16x32_bf16 v[22:25], v[194:197], v[176:179], v[22:25]
	v_mfma_f32_16x16x32_bf16 v[18:21], v[202:205], v[176:179], v[18:21]
	v_mfma_f32_16x16x32_bf16 v[6:9], v[194:197], v[184:187], v[6:9]
	v_mfma_f32_16x16x32_bf16 v[2:5], v[202:205], v[184:187], v[2:5]
	v_mfma_f32_16x16x32_bf16 v[54:57], v[198:201], v[162:165], v[54:57]
	v_mfma_f32_16x16x32_bf16 v[50:53], v[206:209], v[162:165], v[50:53]
	v_mfma_f32_16x16x32_bf16 v[38:41], v[198:201], v[172:175], v[38:41]
	v_mfma_f32_16x16x32_bf16 v[34:37], v[206:209], v[172:175], v[34:37]
	v_mfma_f32_16x16x32_bf16 v[22:25], v[198:201], v[180:183], v[22:25]
	v_mfma_f32_16x16x32_bf16 v[18:21], v[206:209], v[180:183], v[18:21]
	v_mfma_f32_16x16x32_bf16 v[6:9], v[198:201], v[190:193], v[6:9]
	v_mfma_f32_16x16x32_bf16 v[2:5], v[206:209], v[190:193], v[2:5]
	s_barrier
	s_add_u32 s92, s92, 0x40000
	s_addc_u32 s93, s93, 0
	s_mov_b32 m0, s43
	ds_read_b128 v[158:161], v171 offset:32768
	ds_read_b128 v[162:165], v171 offset:33792
	ds_read_b128 v[166:169], v171 offset:34816
	ds_read_b128 v[172:175], v171 offset:35840
	ds_read_b128 v[176:179], v171 offset:36864
	ds_read_b128 v[180:183], v171 offset:37888
	ds_read_b128 v[184:187], v171 offset:38912
	ds_read_b128 v[190:193], v171 offset:39936
	global_load_lds_dwordx4 v146, s[92:93]
	s_mov_b32 m0, s44
	s_nop 0
	global_load_lds_dwordx4 v150, s[92:93]
	s_waitcnt lgkmcnt(8)
	s_barrier
	s_waitcnt lgkmcnt(0)
	v_mfma_f32_16x16x32_bf16 v[126:129], v[130:133], v[158:161], v[126:129]
	v_mfma_f32_16x16x32_bf16 v[122:125], v[138:141], v[158:161], v[122:125]
	v_mfma_f32_16x16x32_bf16 v[110:113], v[130:133], v[166:169], v[110:113]
	v_mfma_f32_16x16x32_bf16 v[106:109], v[138:141], v[166:169], v[106:109]
	v_mfma_f32_16x16x32_bf16 v[94:97], v[130:133], v[176:179], v[94:97]
	v_mfma_f32_16x16x32_bf16 v[90:93], v[138:141], v[176:179], v[90:93]
	v_mfma_f32_16x16x32_bf16 v[78:81], v[130:133], v[184:187], v[78:81]
	v_mfma_f32_16x16x32_bf16 v[74:77], v[138:141], v[184:187], v[74:77]
	v_mfma_f32_16x16x32_bf16 v[126:129], v[134:137], v[162:165], v[126:129]
	v_mfma_f32_16x16x32_bf16 v[122:125], v[142:145], v[162:165], v[122:125]
	v_mfma_f32_16x16x32_bf16 v[110:113], v[134:137], v[172:175], v[110:113]
	v_mfma_f32_16x16x32_bf16 v[106:109], v[142:145], v[172:175], v[106:109]
	v_mfma_f32_16x16x32_bf16 v[94:97], v[134:137], v[180:183], v[94:97]
	v_mfma_f32_16x16x32_bf16 v[90:93], v[142:145], v[180:183], v[90:93]
	v_mfma_f32_16x16x32_bf16 v[78:81], v[134:137], v[190:193], v[78:81]
	v_mfma_f32_16x16x32_bf16 v[74:77], v[142:145], v[190:193], v[74:77]
	s_barrier
	s_add_i32 s92, 0, 0x1c000
	s_add_i32 s87, s87, s38
	v_add_u32_e32 v0, s92, v170
	v_lshl_add_u64 v[210:211], v[210:211], 0, s[40:41]
	s_mov_b32 m0, s87
	ds_read_b128 v[194:197], v0
	ds_read_b128 v[198:201], v0 offset:1024
	ds_read_b128 v[202:205], v0 offset:2048
	ds_read_b128 v[206:209], v0 offset:3072
	global_load_lds_dwordx4 v[210:211], off
	s_add_i32 m0, s87, 0x2000
	v_lshl_add_u64 v[210:211], v[212:213], 0, s[40:41]
	global_load_lds_dwordx4 v[210:211], off
	s_barrier
	s_waitcnt lgkmcnt(0)
	v_mfma_f32_16x16x32_bf16 v[118:121], v[194:197], v[158:161], v[118:121]
	v_mfma_f32_16x16x32_bf16 v[114:117], v[202:205], v[158:161], v[114:117]
	v_mfma_f32_16x16x32_bf16 v[102:105], v[194:197], v[166:169], v[102:105]
	v_mfma_f32_16x16x32_bf16 v[98:101], v[202:205], v[166:169], v[98:101]
	v_mfma_f32_16x16x32_bf16 v[86:89], v[194:197], v[176:179], v[86:89]
	v_mfma_f32_16x16x32_bf16 v[82:85], v[202:205], v[176:179], v[82:85]
	v_mfma_f32_16x16x32_bf16 v[70:73], v[194:197], v[184:187], v[70:73]
	v_mfma_f32_16x16x32_bf16 v[66:69], v[202:205], v[184:187], v[66:69]
	v_mfma_f32_16x16x32_bf16 v[118:121], v[198:201], v[162:165], v[118:121]
	v_mfma_f32_16x16x32_bf16 v[114:117], v[206:209], v[162:165], v[114:117]
	v_mfma_f32_16x16x32_bf16 v[102:105], v[198:201], v[172:175], v[102:105]
	v_mfma_f32_16x16x32_bf16 v[98:101], v[206:209], v[172:175], v[98:101]
	v_mfma_f32_16x16x32_bf16 v[86:89], v[198:201], v[180:183], v[86:89]
	v_mfma_f32_16x16x32_bf16 v[82:85], v[206:209], v[180:183], v[82:85]
	v_mfma_f32_16x16x32_bf16 v[70:73], v[198:201], v[190:193], v[70:73]
	v_mfma_f32_16x16x32_bf16 v[66:69], v[206:209], v[190:193], v[66:69]
	s_mov_b32 m0, s60
	v_lshl_add_u64 v[210:211], v[214:215], 0, s[40:41]
	s_barrier
	ds_read_b128 v[158:161], v171 offset:49152
	ds_read_b128 v[162:165], v171 offset:50176
	ds_read_b128 v[166:169], v171 offset:51200
	ds_read_b128 v[172:175], v171 offset:52224
	ds_read_b128 v[176:179], v171 offset:53248
	ds_read_b128 v[180:183], v171 offset:54272
	ds_read_b128 v[184:187], v171 offset:55296
	ds_read_b128 v[190:193], v171 offset:56320
	global_load_lds_dwordx4 v[210:211], off
	s_mov_b32 m0, s61
	v_lshl_add_u64 v[210:211], v[216:217], 0, s[40:41]
	global_load_lds_dwordx4 v[210:211], off
	s_waitcnt vmcnt(10)
	s_barrier
	s_waitcnt lgkmcnt(0)
	v_mfma_f32_16x16x32_bf16 v[62:65], v[130:133], v[158:161], v[62:65]
	v_mfma_f32_16x16x32_bf16 v[58:61], v[138:141], v[158:161], v[58:61]
	v_mfma_f32_16x16x32_bf16 v[46:49], v[130:133], v[166:169], v[46:49]
	v_mfma_f32_16x16x32_bf16 v[42:45], v[138:141], v[166:169], v[42:45]
	v_mfma_f32_16x16x32_bf16 v[30:33], v[130:133], v[176:179], v[30:33]
	v_mfma_f32_16x16x32_bf16 v[26:29], v[138:141], v[176:179], v[26:29]
	v_mfma_f32_16x16x32_bf16 v[14:17], v[130:133], v[184:187], v[14:17]
	v_mfma_f32_16x16x32_bf16 v[10:13], v[138:141], v[184:187], v[10:13]
	v_mfma_f32_16x16x32_bf16 v[62:65], v[134:137], v[162:165], v[62:65]
	v_mfma_f32_16x16x32_bf16 v[58:61], v[142:145], v[162:165], v[58:61]
	v_mfma_f32_16x16x32_bf16 v[46:49], v[134:137], v[172:175], v[46:49]
	v_mfma_f32_16x16x32_bf16 v[42:45], v[142:145], v[172:175], v[42:45]
	v_mfma_f32_16x16x32_bf16 v[30:33], v[134:137], v[180:183], v[30:33]
	v_mfma_f32_16x16x32_bf16 v[26:29], v[142:145], v[180:183], v[26:29]
	v_mfma_f32_16x16x32_bf16 v[14:17], v[134:137], v[190:193], v[14:17]
	v_mfma_f32_16x16x32_bf16 v[10:13], v[142:145], v[190:193], v[10:13]
	s_barrier
	s_add_u32 s90, s90, 0x40080
	s_addc_u32 s91, s91, 0
	s_add_i32 s87, s92, s38
	s_mov_b32 m0, s87
	s_nop 0
	global_load_lds_dwordx4 v148, s[90:91]
	s_add_i32 m0, s87, 0x2000
	s_nop 0
	global_load_lds_dwordx4 v152, s[90:91]
	s_add_i32 s94, 0, 0x10000
	v_add_u32_e32 v0, s94, v170
	ds_read_b128 v[130:133], v0
	ds_read_b128 v[134:137], v0 offset:1024
	ds_read_b128 v[138:141], v0 offset:2048
	ds_read_b128 v[142:145], v0 offset:3072
	s_waitcnt vmcnt(6)
	s_barrier
	v_mfma_f32_16x16x32_bf16 v[54:57], v[194:197], v[158:161], v[54:57]
	v_mfma_f32_16x16x32_bf16 v[50:53], v[202:205], v[158:161], v[50:53]
	v_mfma_f32_16x16x32_bf16 v[38:41], v[194:197], v[166:169], v[38:41]
	v_mfma_f32_16x16x32_bf16 v[34:37], v[202:205], v[166:169], v[34:37]
	v_mfma_f32_16x16x32_bf16 v[22:25], v[194:197], v[176:179], v[22:25]
	v_mfma_f32_16x16x32_bf16 v[18:21], v[202:205], v[176:179], v[18:21]
	v_mfma_f32_16x16x32_bf16 v[6:9], v[194:197], v[184:187], v[6:9]
	v_mfma_f32_16x16x32_bf16 v[2:5], v[202:205], v[184:187], v[2:5]
	v_mfma_f32_16x16x32_bf16 v[54:57], v[198:201], v[162:165], v[54:57]
	v_mfma_f32_16x16x32_bf16 v[50:53], v[206:209], v[162:165], v[50:53]
	v_mfma_f32_16x16x32_bf16 v[38:41], v[198:201], v[172:175], v[38:41]
	v_mfma_f32_16x16x32_bf16 v[34:37], v[206:209], v[172:175], v[34:37]
	v_mfma_f32_16x16x32_bf16 v[22:25], v[198:201], v[180:183], v[22:25]
	v_mfma_f32_16x16x32_bf16 v[18:21], v[206:209], v[180:183], v[18:21]
	v_mfma_f32_16x16x32_bf16 v[6:9], v[198:201], v[190:193], v[6:9]
	v_mfma_f32_16x16x32_bf16 v[2:5], v[206:209], v[190:193], v[2:5]
	s_add_i32 s85, s85, 2
	s_add_u32 s88, s88, 0x100
	s_addc_u32 s89, s89, 0
	s_add_u32 s34, s34, 0x100
	s_addc_u32 s79, s79, 0
	s_add_u32 s87, s88, 0xfffc0080
	s_addc_u32 s90, s89, -1
	s_cmp_eq_u32 s85, 12
	s_cselect_b32 s93, s13, s90
	s_cselect_b32 s92, s22, s87
	s_cselect_b32 s91, s7, s79
	s_cselect_b32 s90, s23, s34
	s_cmp_gt_u32 s85, 13
	s_barrier
	s_cbranch_scc0 .LBB0_1209
	s_waitcnt lgkmcnt(0)
	v_mov_b32_e32 v131, v252
	s_lshl_b32 s7, s86, 8
	v_and_b32_e32 v130, 63, v131
	v_or_b32_e32 v0, s72, v130
	v_lshrrev_b32_e32 v0, 1, v0
	v_and_or_b32 v132, v0, 63, s73
	v_add_u32_e32 v134, s7, v132
	v_ashrrev_i32_e32 v135, 31, v134
	v_and_b32_e32 v142, 1, v131
	v_lshlrev_b64 v[134:135], 6, v[134:135]
	v_lshl_add_u64 v[134:135], s[82:83], 0, v[134:135]
	v_lshlrev_b32_e32 v0, 5, v142
	v_lshl_add_u64 v[138:139], v[134:135], 0, v[0:1]
	global_load_dwordx4 v[134:137], v[138:139], off
	s_nop 0
	global_load_dwordx4 v[138:141], v[138:139], off offset:16
	v_lshlrev_b32_e32 v0, 2, v130
	v_cmp_eq_u32_e32 vcc, 0, v142
	s_waitcnt vmcnt(0)
	v_add_f32_e32 v133, v134, v135
	v_add_f32_e32 v134, v136, v137
	v_add_f32_e32 v135, v138, v139
	v_add_f32_e32 v136, v140, v141
	v_add_f32_e32 v133, v133, v134
	v_add_f32_e32 v134, v135, v136
	v_add_f32_e32 v133, v133, v134
	v_xor_b32_e32 v134, 4, v0
	ds_bpermute_b32 v134, v134, v133
	s_and_saveexec_b64 s[22:23], vcc
	s_cbranch_execz .LBB0_1212
	s_waitcnt lgkmcnt(0)
	v_add_f32_e32 v133, v133, v134
	v_fmamk_f32 v133, v133, 0x3a800000, v224
	s_mov_b32 s13, 0x800000
	v_mul_f32_e32 v134, 0x4b800000, v133
	v_cmp_gt_f32_e32 vcc, s13, v133
	v_lshl_add_u32 v132, v132, 2, 0
	v_add_u32_e32 v132, 0x20000, v132
	v_cndmask_b32_e32 v133, v133, v134, vcc
	v_rsq_f32_e32 v133, v133
	s_nop 0
	v_mul_f32_e32 v134, 0x45800000, v133
	v_cndmask_b32_e32 v133, v133, v134, vcc
	ds_write_b32 v132, v133
